# ad1 + f32->bf16 pack peephole in modulate0/rowpass1/rowpass2: 89 bit-trick pairs (bfe/add3/lshr/and_or, 6 VALU) replaced by v_cvt_pk_bf16_f32, SGPR-hazard nops re-derived
# speedup vs baseline: 1.0063x; 1.0015x over previous
.LBB0_208:
	v_mov_b32_e32 v84, v60
	v_mov_b32_e32 v85, v56
	v_mov_b32_e32 v86, v61
	v_mov_b32_e32 v87, v57
	v_pk_add_f32 v[84:85], v[84:85], v[86:87]
	v_mov_b32_e32 v86, v62
	v_mov_b32_e32 v87, v58
	v_mov_b32_e32 v88, v63
	v_mov_b32_e32 v89, v59
	v_pk_add_f32 v[86:87], v[86:87], v[88:89]
	v_mov_b32_e32 v88, v52
	v_pk_add_f32 v[84:85], v[84:85], v[86:87]
	v_mov_b32_e32 v86, v53
	v_mov_b32_e32 v87, v54
	v_mov_b32_e32 v89, v55
	v_pk_add_f32 v[86:87], v[86:87], v[88:89]
	v_add_f32_e32 v84, 0, v84
	v_pk_add_f32 v[86:87], v[86:87], v[86:87] op_sel:[0,1] op_sel_hi:[1,0]
	v_add_f32_e32 v84, v84, v85
	v_add_f32_e32 v88, v48, v49
	v_add_f32_e32 v90, v50, v51
	v_mov_b32_e32 v85, v44
	v_mov_b32_e32 v87, v45
	v_mov_b32_e32 v89, v46
	v_mov_b32_e32 v91, v47
	v_pk_add_f32 v[84:85], v[84:85], v[86:87]
	v_pk_add_f32 v[86:87], v[88:89], v[90:91]
	v_mov_b32_e32 v88, v40
	v_pk_add_f32 v[84:85], v[84:85], v[86:87]
	v_mov_b32_e32 v86, v41
	v_mov_b32_e32 v87, v42
	v_mov_b32_e32 v89, v43
	v_pk_add_f32 v[86:87], v[86:87], v[88:89]
	v_pk_add_f32 v[84:85], v[84:85], v[84:85] op_sel:[0,1] op_sel_hi:[1,0]
	v_pk_add_f32 v[86:87], v[86:87], v[86:87] op_sel:[0,1] op_sel_hi:[1,0]
	v_add_f32_e32 v88, v36, v37
	v_add_f32_e32 v90, v38, v39
	v_mov_b32_e32 v85, v32
	v_mov_b32_e32 v87, v33
	v_mov_b32_e32 v89, v34
	v_mov_b32_e32 v91, v35
	v_pk_add_f32 v[84:85], v[84:85], v[86:87]
	v_pk_add_f32 v[86:87], v[88:89], v[90:91]
	s_nop 0
	v_pk_add_f32 v[84:85], v[84:85], v[86:87]
	s_nop 0
	v_add_f32_e32 v84, v84, v85
	ds_bpermute_b32 v85, v65, v84
	s_waitcnt lgkmcnt(0)
	v_add_f32_e32 v84, v84, v85
	ds_bpermute_b32 v85, v72, v84
	s_waitcnt lgkmcnt(0)
	v_add_f32_e32 v84, v84, v85
	ds_bpermute_b32 v85, v73, v84
	s_waitcnt lgkmcnt(0)
	v_add_f32_e32 v84, v84, v85
	ds_bpermute_b32 v85, v74, v84
	s_waitcnt lgkmcnt(0)
	v_add_f32_e32 v84, v84, v85
	ds_bpermute_b32 v85, v75, v84
	s_waitcnt lgkmcnt(0)
	v_add_f32_e32 v84, v84, v85
	ds_bpermute_b32 v85, v76, v84
	s_waitcnt lgkmcnt(0)
	v_add_f32_e32 v90, v84, v85
	v_fmamk_f32 v61, v90, 0xba000000, v61
	v_fmamk_f32 v57, v90, 0xba000000, v57
	v_fmamk_f32 v63, v90, 0xba000000, v63
	v_fmac_f32_e32 v60, 0xba000000, v90
	v_fmamk_f32 v93, v90, 0xba000000, v59
	v_fmac_f32_e32 v56, 0xba000000, v90
	v_mov_b32_e32 v84, v61
	v_mov_b32_e32 v85, v57
	v_fmamk_f32 v62, v90, 0xba000000, v62
	v_fmamk_f32 v92, v90, 0xba000000, v58
	v_mov_b32_e32 v58, v60
	v_mov_b32_e32 v59, v56
	v_pk_mul_f32 v[84:85], v[84:85], v[84:85]
	v_mov_b32_e32 v86, v63
	v_mov_b32_e32 v87, v93
	v_pk_fma_f32 v[58:59], v[58:59], v[58:59], v[84:85]
	v_mov_b32_e32 v84, v62
	v_mov_b32_e32 v85, v92
	v_pk_mul_f32 v[86:87], v[86:87], v[86:87]
	v_fmamk_f32 v95, v90, 0xba000000, v53
	v_pk_fma_f32 v[84:85], v[84:85], v[84:85], v[86:87]
	v_fmamk_f32 v94, v90, 0xba000000, v52
	v_fmamk_f32 v55, v90, 0xba000000, v55
	v_fmac_f32_e32 v54, 0xba000000, v90
	v_pk_add_f32 v[58:59], v[58:59], v[84:85]
	v_pk_mul_f32 v[52:53], v[54:55], v[54:55]
	v_pk_mul_f32 v[84:85], v[94:95], v[94:95]
	v_fmac_f32_e32 v50, 0xba000000, v90
	v_pk_mov_b32 v[86:87], v[84:85], v[52:53] op_sel:[1,0]
	v_mov_b32_e32 v85, v53
	v_pk_add_f32 v[52:53], v[86:87], v[84:85]
	v_fmamk_f32 v51, v90, 0xba000000, v51
	v_pk_add_f32 v[84:85], v[52:53], v[52:53] op_sel_hi:[0,1]
	v_fmamk_f32 v52, v90, 0xba000000, v48
	v_fmamk_f32 v53, v90, 0xba000000, v49
	v_mul_f32_e32 v48, v52, v52
	v_pk_fma_f32 v[86:87], v[52:53], v[52:53], v[48:49] op_sel_hi:[1,1,0]
	v_mul_f32_e32 v48, v50, v50
	v_pk_add_f32 v[58:59], v[58:59], v[58:59] op_sel_hi:[0,1]
	v_pk_fma_f32 v[88:89], v[50:51], v[50:51], v[48:49] op_sel_hi:[1,1,0]
	v_fmamk_f32 v49, v90, 0xba000000, v47
	v_fmamk_f32 v48, v90, 0xba000000, v46
	v_fmamk_f32 v45, v90, 0xba000000, v45
	v_fmac_f32_e32 v44, 0xba000000, v90
	v_mul_f32_e32 v86, v44, v44
	v_mul_f32_e32 v88, v45, v45
	v_mul_f32_e32 v84, v48, v48
	v_mul_f32_e32 v58, v49, v49
	v_pk_add_f32 v[46:47], v[86:87], v[88:89]
	v_pk_add_f32 v[58:59], v[84:85], v[58:59]
	v_fmamk_f32 v41, v90, 0xba000000, v41
	v_pk_add_f32 v[46:47], v[46:47], v[58:59]
	v_fmamk_f32 v40, v90, 0xba000000, v40
	v_fmamk_f32 v43, v90, 0xba000000, v43
	v_fmac_f32_e32 v42, 0xba000000, v90
	v_pk_add_f32 v[46:47], v[46:47], v[46:47] op_sel_hi:[0,1]
	v_pk_mul_f32 v[58:59], v[42:43], v[42:43]
	v_pk_mul_f32 v[84:85], v[40:41], v[40:41]
	v_fmamk_f32 v36, v90, 0xba000000, v36
	v_pk_mov_b32 v[86:87], v[84:85], v[58:59] op_sel:[1,0]
	v_mov_b32_e32 v85, v59
	v_fmamk_f32 v37, v90, 0xba000000, v37
	v_fmac_f32_e32 v38, 0xba000000, v90
	v_mul_f32_e32 v46, v36, v36
	v_pk_add_f32 v[58:59], v[86:87], v[84:85]
	v_fmamk_f32 v39, v90, 0xba000000, v39
	v_pk_fma_f32 v[84:85], v[36:37], v[36:37], v[46:47] op_sel_hi:[1,1,0]
	v_mul_f32_e32 v46, v38, v38
	v_pk_add_f32 v[58:59], v[58:59], v[58:59] op_sel_hi:[0,1]
	v_pk_fma_f32 v[86:87], v[38:39], v[38:39], v[46:47] op_sel_hi:[1,1,0]
	v_fmamk_f32 v35, v90, 0xba000000, v35
	v_fmamk_f32 v34, v90, 0xba000000, v34
	v_fmamk_f32 v33, v90, 0xba000000, v33
	v_fmac_f32_e32 v32, 0xba000000, v90
	v_mul_f32_e32 v84, v32, v32
	v_mul_f32_e32 v86, v33, v33
	v_mul_f32_e32 v58, v34, v34
	v_mul_f32_e32 v46, v35, v35
	v_pk_add_f32 v[84:85], v[84:85], v[86:87]
	v_pk_add_f32 v[46:47], v[58:59], v[46:47]
	s_nop 0
	v_pk_add_f32 v[46:47], v[84:85], v[46:47]
	s_nop 0
	v_add_f32_e32 v46, v46, v47
	ds_bpermute_b32 v47, v65, v46
	s_waitcnt lgkmcnt(0)
	v_add_f32_e32 v46, v46, v47
	ds_bpermute_b32 v47, v72, v46
	s_waitcnt lgkmcnt(0)
	v_add_f32_e32 v46, v46, v47
	ds_bpermute_b32 v47, v73, v46
	s_waitcnt lgkmcnt(0)
	v_add_f32_e32 v46, v46, v47
	ds_bpermute_b32 v47, v74, v46
	s_waitcnt lgkmcnt(0)
	v_add_f32_e32 v46, v46, v47
	ds_bpermute_b32 v47, v75, v46
	s_waitcnt lgkmcnt(0)
	v_add_f32_e32 v46, v46, v47
	ds_bpermute_b32 v47, v76, v46
	s_waitcnt lgkmcnt(0)
	v_add_f32_e32 v46, v46, v47
	v_fmamk_f32 v46, v46, 0x3a000000, v82
	v_mul_f32_e32 v47, 0x4f800000, v46
	v_cmp_gt_f32_e32 vcc, s3, v46
	s_nop 1
	v_cndmask_b32_e32 v46, v46, v47, vcc
	v_sqrt_f32_e32 v47, v46
	s_nop 0
	v_add_u32_e32 v58, -1, v47
	v_fma_f32 v59, -v58, v47, v46
	v_cmp_ge_f32_e64 s[4:5], 0, v59
	v_add_u32_e32 v59, 1, v47
	s_nop 0
	v_cndmask_b32_e64 v58, v47, v58, s[4:5]
	v_fma_f32 v47, -v59, v47, v46
	v_cmp_lt_f32_e64 s[4:5], 0, v47
	s_nop 1
	v_cndmask_b32_e64 v47, v58, v59, s[4:5]
	v_mul_f32_e32 v58, 0x37800000, v47
	v_cndmask_b32_e32 v47, v47, v58, vcc
	v_cmp_class_f32_e32 vcc, v46, v83
	s_nop 1
	v_cndmask_b32_e32 v46, v47, v46, vcc
	v_div_scale_f32 v47, s[4:5], v46, v46, 1.0
	v_rcp_f32_e32 v58, v47
	s_min_i32 s4, s20, 0x4000
	s_and_b32 s4, s4, 0x3ffff000
	v_fma_f32 v59, -v47, v58, 1.0
	v_fmac_f32_e32 v58, v59, v58
	v_div_scale_f32 v59, vcc, 1.0, v46, 1.0
	v_mul_f32_e32 v84, v59, v58
	v_fma_f32 v85, -v47, v84, v59
	v_fmac_f32_e32 v84, v85, v58
	v_fma_f32 v47, -v47, v84, v59
	v_div_fmas_f32 v47, v47, v58, v84
	v_div_fixup_f32 v46, v47, v46, 1.0
	v_lshl_add_u32 v47, s4, 2, v77
	ds_read_b128 v[84:87], v47 offset:8192
	ds_read_b128 v[88:91], v47
	v_pk_mul_f32 v[96:97], v[60:61], v[46:47] op_sel_hi:[1,0]
	ds_read_b128 v[58:61], v47 offset:9216
	v_pk_mul_f32 v[62:63], v[62:63], v[46:47] op_sel_hi:[1,0]
	s_waitcnt lgkmcnt(2)
	v_pk_add_f32 v[100:101], v[84:85], 1.0 op_sel_hi:[1,0]
	v_pk_add_f32 v[98:99], v[86:87], 1.0 op_sel_hi:[1,0]
	ds_read_b128 v[84:87], v47 offset:1024
	s_waitcnt lgkmcnt(2)
	v_pk_fma_f32 v[88:89], v[100:101], v[96:97], v[88:89]
	v_pk_fma_f32 v[62:63], v[98:99], v[62:63], v[90:91]
	v_cvt_pk_bf16_f32 v88, v88, v89
	v_pk_mul_f32 v[56:57], v[56:57], v[46:47] op_sel_hi:[1,0]
	s_waitcnt lgkmcnt(1)
	v_pk_add_f32 v[58:59], v[58:59], 1.0 op_sel_hi:[1,0]
	s_waitcnt lgkmcnt(0)
	v_pk_fma_f32 v[56:57], v[58:59], v[56:57], v[84:85]
	v_cvt_pk_bf16_f32 v89, v62, v63
	v_pk_mul_f32 v[62:63], v[92:93], v[46:47] op_sel_hi:[1,0]
	v_pk_add_f32 v[60:61], v[60:61], 1.0 op_sel_hi:[1,0]
	v_pk_fma_f32 v[60:61], v[60:61], v[62:63], v[86:87]
	v_cvt_pk_bf16_f32 v56, v56, v57
	v_cvt_pk_bf16_f32 v57, v60, v61
	global_store_dwordx2 v[70:71], v[88:89], off
	global_store_dwordx2 v[70:71], v[56:57], off offset:512
	ds_read_b128 v[56:59], v47 offset:10240
	ds_read_b128 v[60:63], v47 offset:2048
	v_pk_mul_f32 v[88:89], v[94:95], v[46:47] op_sel_hi:[1,0]
	v_pk_mul_f32 v[90:91], v[54:55], v[46:47] op_sel_hi:[1,0]
	ds_read_b128 v[84:87], v47 offset:11264
	s_waitcnt lgkmcnt(2)
	v_pk_add_f32 v[92:93], v[56:57], 1.0 op_sel_hi:[1,0]
	v_pk_add_f32 v[58:59], v[58:59], 1.0 op_sel_hi:[1,0]
	s_waitcnt lgkmcnt(1)
	v_pk_fma_f32 v[60:61], v[92:93], v[88:89], v[60:61]
	v_pk_fma_f32 v[58:59], v[58:59], v[90:91], v[62:63]
	ds_read_b128 v[54:57], v47 offset:3072
	v_cvt_pk_bf16_f32 v60, v60, v61
	v_cvt_pk_bf16_f32 v61, v58, v59
	global_store_dwordx2 v[70:71], v[60:61], off offset:1024
	v_pk_mul_f32 v[52:53], v[52:53], v[46:47] op_sel_hi:[1,0]
	s_waitcnt lgkmcnt(1)
	v_pk_add_f32 v[60:61], v[84:85], 1.0 op_sel_hi:[1,0]
	v_pk_mul_f32 v[50:51], v[50:51], v[46:47] op_sel_hi:[1,0]
	s_waitcnt lgkmcnt(0)
	v_pk_fma_f32 v[52:53], v[60:61], v[52:53], v[54:55]
	v_pk_add_f32 v[58:59], v[86:87], 1.0 op_sel_hi:[1,0]
	v_pk_fma_f32 v[50:51], v[58:59], v[50:51], v[56:57]
	v_cvt_pk_bf16_f32 v52, v52, v53
	v_cvt_pk_bf16_f32 v53, v50, v51
	global_store_dwordx2 v[70:71], v[52:53], off offset:1536
	ds_read_b128 v[50:53], v47 offset:12288
	ds_read_b128 v[54:57], v47 offset:4096
	v_pk_mul_f32 v[44:45], v[44:45], v[46:47] op_sel_hi:[1,0]
	v_pk_mul_f32 v[62:63], v[48:49], v[46:47] op_sel_hi:[1,0]
	ds_read_b128 v[58:61], v47 offset:13312
	s_waitcnt lgkmcnt(2)
	v_pk_add_f32 v[84:85], v[50:51], 1.0 op_sel_hi:[1,0]
	v_pk_add_f32 v[52:53], v[52:53], 1.0 op_sel_hi:[1,0]
	s_waitcnt lgkmcnt(1)
	v_pk_fma_f32 v[44:45], v[84:85], v[44:45], v[54:55]
	ds_read_b128 v[48:51], v47 offset:5120
	v_pk_fma_f32 v[52:53], v[52:53], v[62:63], v[56:57]
	v_cvt_pk_bf16_f32 v44, v44, v45
	v_cvt_pk_bf16_f32 v45, v52, v53
	v_pk_mul_f32 v[40:41], v[40:41], v[46:47] op_sel_hi:[1,0]
	s_waitcnt lgkmcnt(1)
	v_pk_add_f32 v[52:53], v[58:59], 1.0 op_sel_hi:[1,0]
	global_store_dwordx2 v[70:71], v[44:45], off offset:2048
	v_pk_mul_f32 v[42:43], v[42:43], v[46:47] op_sel_hi:[1,0]
	v_pk_add_f32 v[44:45], v[60:61], 1.0 op_sel_hi:[1,0]
	s_waitcnt lgkmcnt(0)
	v_pk_fma_f32 v[40:41], v[52:53], v[40:41], v[48:49]
	v_pk_fma_f32 v[42:43], v[44:45], v[42:43], v[50:51]
	v_cvt_pk_bf16_f32 v40, v40, v41
	v_cvt_pk_bf16_f32 v41, v42, v43
	global_store_dwordx2 v[70:71], v[40:41], off offset:2560
	ds_read_b128 v[40:43], v47 offset:14336
	ds_read_b128 v[48:51], v47 offset:6144
	v_pk_mul_f32 v[44:45], v[36:37], v[46:47] op_sel_hi:[1,0]
	v_pk_mul_f32 v[52:53], v[38:39], v[46:47] op_sel_hi:[1,0]
	ds_read_b128 v[36:39], v47 offset:15360
	s_waitcnt lgkmcnt(2)
	v_pk_add_f32 v[56:57], v[40:41], 1.0 op_sel_hi:[1,0]
	v_pk_add_f32 v[54:55], v[42:43], 1.0 op_sel_hi:[1,0]
	s_waitcnt lgkmcnt(1)
	v_pk_fma_f32 v[44:45], v[56:57], v[44:45], v[48:49]
	ds_read_b128 v[40:43], v47 offset:7168
	v_pk_fma_f32 v[50:51], v[54:55], v[52:53], v[50:51]
	v_bfe_u32 v47, v51, 16, 1
	v_add3_u32 v47, v51, v47, s28
	v_pk_mul_f32 v[32:33], v[32:33], v[46:47] op_sel_hi:[1,0]
	s_waitcnt lgkmcnt(1)
	v_pk_add_f32 v[36:37], v[36:37], 1.0 op_sel_hi:[1,0]
	v_pk_mul_f32 v[34:35], v[34:35], v[46:47] op_sel_hi:[1,0]
	s_waitcnt lgkmcnt(0)
	v_pk_fma_f32 v[32:33], v[36:37], v[32:33], v[40:41]
	v_pk_add_f32 v[38:39], v[38:39], 1.0 op_sel_hi:[1,0]
	v_pk_fma_f32 v[34:35], v[38:39], v[34:35], v[42:43]
	v_cvt_pk_bf16_f32 v44, v44, v45
	v_bfe_u32 v45, v50, 16, 1
	v_cvt_pk_bf16_f32 v32, v32, v33
	v_add3_u32 v45, v50, v45, s28
	v_lshrrev_b32_e32 v45, 16, v45
	v_and_or_b32 v45, v47, s29, v45
	v_cvt_pk_bf16_f32 v33, v34, v35
	s_andn2_b64 vcc, exec, s[24:25]
	global_store_dwordx2 v[70:71], v[44:45], off offset:3072
	global_store_dwordx2 v[70:71], v[32:33], off offset:3584
	s_cbranch_vccnz .LBB0_197
	v_mov_b32_e32 v32, v4
	v_mov_b32_e32 v33, v0
	v_mov_b32_e32 v34, v5
	v_mov_b32_e32 v35, v1
	v_pk_add_f32 v[32:33], v[32:33], v[34:35]
	v_mov_b32_e32 v34, v6
	v_mov_b32_e32 v35, v2
	v_mov_b32_e32 v36, v7
	v_mov_b32_e32 v37, v3
	v_pk_add_f32 v[34:35], v[34:35], v[36:37]
	v_mov_b32_e32 v36, v8
	v_pk_add_f32 v[32:33], v[32:33], v[34:35]
	v_mov_b32_e32 v34, v9
	v_mov_b32_e32 v35, v10
	v_mov_b32_e32 v37, v11
	v_pk_add_f32 v[34:35], v[34:35], v[36:37]
	v_add_f32_e32 v33, 0, v33
	v_pk_add_f32 v[34:35], v[34:35], v[34:35] op_sel_hi:[0,1]
	v_add_f32_e32 v33, v32, v33
	v_add_f32_e32 v37, v12, v13
	v_add_f32_e32 v39, v14, v15
	v_mov_b32_e32 v36, v16
	v_mov_b32_e32 v38, v17
	v_mov_b32_e32 v34, v18
	v_mov_b32_e32 v32, v19
	v_pk_add_f32 v[36:37], v[36:37], v[38:39]
	v_pk_add_f32 v[32:33], v[34:35], v[32:33]
	v_mov_b32_e32 v34, v21
	v_pk_add_f32 v[32:33], v[36:37], v[32:33]
	v_mov_b32_e32 v35, v22
	v_mov_b32_e32 v36, v20
	v_mov_b32_e32 v37, v23
	v_pk_add_f32 v[34:35], v[34:35], v[36:37]
	v_pk_add_f32 v[32:33], v[32:33], v[32:33] op_sel_hi:[0,1]
	v_pk_add_f32 v[34:35], v[34:35], v[34:35] op_sel_hi:[0,1]
	v_add_f32_e32 v37, v24, v25
	v_add_f32_e32 v39, v26, v27
	v_mov_b32_e32 v36, v28
	v_mov_b32_e32 v38, v29
	v_mov_b32_e32 v34, v30
	v_mov_b32_e32 v32, v31
	v_pk_add_f32 v[36:37], v[36:37], v[38:39]
	v_pk_add_f32 v[32:33], v[34:35], v[32:33]
	s_ashr_i32 s23, s22, 31
	v_pk_add_f32 v[32:33], v[36:37], v[32:33]
	s_nop 0
	v_add_f32_e32 v32, v32, v33
	ds_bpermute_b32 v33, v65, v32
	s_waitcnt lgkmcnt(0)
	v_add_f32_e32 v32, v32, v33
	ds_bpermute_b32 v33, v72, v32
	s_waitcnt lgkmcnt(0)
	v_add_f32_e32 v32, v32, v33
	ds_bpermute_b32 v33, v73, v32
	s_waitcnt lgkmcnt(0)
	v_add_f32_e32 v32, v32, v33
	ds_bpermute_b32 v33, v74, v32
	s_waitcnt lgkmcnt(0)
	v_add_f32_e32 v32, v32, v33
	ds_bpermute_b32 v33, v75, v32
	s_waitcnt lgkmcnt(0)
	v_add_f32_e32 v32, v32, v33
	ds_bpermute_b32 v33, v76, v32
	s_waitcnt lgkmcnt(0)
	v_add_f32_e32 v60, v32, v33
	v_fmamk_f32 v85, v60, 0xba000000, v1
	v_fmamk_f32 v95, v60, 0xba000000, v5
	v_fmamk_f32 v63, v60, 0xba000000, v3
	v_fmamk_f32 v84, v60, 0xba000000, v0
	v_fmamk_f32 v93, v60, 0xba000000, v7
	v_fmamk_f32 v94, v60, 0xba000000, v4
	v_mov_b32_e32 v34, v85
	v_mov_b32_e32 v35, v95
	v_fmamk_f32 v62, v60, 0xba000000, v2
	v_fmamk_f32 v92, v60, 0xba000000, v6
	v_mov_b32_e32 v32, v84
	v_mov_b32_e32 v33, v94
	v_pk_mul_f32 v[34:35], v[34:35], v[34:35]
	v_mov_b32_e32 v36, v63
	v_mov_b32_e32 v37, v93
	v_pk_fma_f32 v[32:33], v[32:33], v[32:33], v[34:35]
	v_mov_b32_e32 v34, v62
	v_mov_b32_e32 v35, v92
	v_pk_mul_f32 v[36:37], v[36:37], v[36:37]
	v_fmamk_f32 v97, v60, 0xba000000, v9
	v_pk_fma_f32 v[34:35], v[34:35], v[34:35], v[36:37]
	v_fmamk_f32 v96, v60, 0xba000000, v8
	v_pk_add_f32 v[32:33], v[32:33], v[34:35]
	v_fmamk_f32 v99, v60, 0xba000000, v11
	v_fmamk_f32 v98, v60, 0xba000000, v10
	v_pk_add_f32 v[32:33], v[32:33], v[32:33] op_sel_hi:[0,1]
	v_pk_mul_f32 v[34:35], v[98:99], v[98:99]
	v_pk_mul_f32 v[36:37], v[96:97], v[96:97]
	v_fmamk_f32 v50, v60, 0xba000000, v12
	v_pk_mov_b32 v[38:39], v[36:37], v[34:35] op_sel:[1,0]
	v_mov_b32_e32 v37, v35
	v_fmamk_f32 v51, v60, 0xba000000, v13
	v_fmamk_f32 v52, v60, 0xba000000, v14
	v_mul_f32_e32 v32, v50, v50
	v_pk_add_f32 v[34:35], v[38:39], v[36:37]
	v_fmamk_f32 v53, v60, 0xba000000, v15
	v_pk_fma_f32 v[36:37], v[50:51], v[50:51], v[32:33] op_sel_hi:[1,1,0]
	v_mul_f32_e32 v32, v52, v52
	v_pk_add_f32 v[34:35], v[34:35], v[34:35] op_sel_hi:[0,1]
	v_pk_fma_f32 v[38:39], v[52:53], v[52:53], v[32:33] op_sel_hi:[1,1,0]
	v_fmamk_f32 v47, v60, 0xba000000, v19
	v_fmamk_f32 v46, v60, 0xba000000, v18
	v_fmamk_f32 v49, v60, 0xba000000, v17
	v_fmamk_f32 v48, v60, 0xba000000, v16
	v_mul_f32_e32 v36, v48, v48
	v_mul_f32_e32 v38, v49, v49
	v_mul_f32_e32 v34, v46, v46
	v_mul_f32_e32 v32, v47, v47
	v_pk_add_f32 v[36:37], v[36:37], v[38:39]
	v_pk_add_f32 v[32:33], v[34:35], v[32:33]
	v_fmamk_f32 v41, v60, 0xba000000, v21
	v_pk_add_f32 v[32:33], v[36:37], v[32:33]
	v_fmamk_f32 v40, v60, 0xba000000, v20
	v_fmamk_f32 v43, v60, 0xba000000, v23
	v_fmamk_f32 v42, v60, 0xba000000, v22
	v_pk_add_f32 v[44:45], v[32:33], v[32:33] op_sel_hi:[0,1]
	v_pk_mul_f32 v[32:33], v[42:43], v[42:43]
	v_pk_mul_f32 v[34:35], v[40:41], v[40:41]
	v_fmamk_f32 v38, v60, 0xba000000, v26
	v_pk_mov_b32 v[36:37], v[34:35], v[32:33] op_sel:[1,0]
	v_mov_b32_e32 v35, v33
	v_pk_add_f32 v[32:33], v[36:37], v[34:35]
	v_fmamk_f32 v36, v60, 0xba000000, v24
	v_pk_add_f32 v[54:55], v[32:33], v[32:33] op_sel_hi:[0,1]
	v_fmamk_f32 v37, v60, 0xba000000, v25
	v_mul_f32_e32 v32, v36, v36
	v_fmamk_f32 v39, v60, 0xba000000, v27
	v_pk_fma_f32 v[56:57], v[36:37], v[36:37], v[32:33] op_sel_hi:[1,1,0]
	v_mul_f32_e32 v32, v38, v38
	v_pk_fma_f32 v[58:59], v[38:39], v[38:39], v[32:33] op_sel_hi:[1,1,0]
	v_fmamk_f32 v33, v60, 0xba000000, v31
	v_fmamk_f32 v32, v60, 0xba000000, v30
	v_fmamk_f32 v35, v60, 0xba000000, v29
	v_fmamk_f32 v34, v60, 0xba000000, v28
	v_mul_f32_e32 v56, v34, v34
	v_mul_f32_e32 v58, v35, v35
	v_mul_f32_e32 v54, v32, v32
	v_mul_f32_e32 v44, v33, v33
	v_pk_add_f32 v[56:57], v[56:57], v[58:59]
	v_pk_add_f32 v[44:45], v[54:55], v[44:45]
	s_nop 0
	v_pk_add_f32 v[44:45], v[56:57], v[44:45]
	s_nop 0
	v_add_f32_e32 v44, v44, v45
	ds_bpermute_b32 v45, v65, v44
	s_waitcnt lgkmcnt(0)
	v_add_f32_e32 v44, v44, v45
	ds_bpermute_b32 v45, v72, v44
	s_waitcnt lgkmcnt(0)
	v_add_f32_e32 v44, v44, v45
	ds_bpermute_b32 v45, v73, v44
	s_waitcnt lgkmcnt(0)
	v_add_f32_e32 v44, v44, v45
	ds_bpermute_b32 v45, v74, v44
	s_waitcnt lgkmcnt(0)
	v_add_f32_e32 v44, v44, v45
	ds_bpermute_b32 v45, v75, v44
	s_waitcnt lgkmcnt(0)
	v_add_f32_e32 v44, v44, v45
	ds_bpermute_b32 v45, v76, v44
	s_waitcnt lgkmcnt(0)
	v_add_f32_e32 v44, v44, v45
	v_fmamk_f32 v44, v44, 0x3a000000, v82
	v_mul_f32_e32 v45, 0x4f800000, v44
	v_cmp_gt_f32_e32 vcc, s3, v44
	s_nop 1
	v_cndmask_b32_e32 v44, v44, v45, vcc
	v_sqrt_f32_e32 v45, v44
	s_nop 0
	v_add_u32_e32 v54, -1, v45
	v_fma_f32 v55, -v54, v45, v44
	v_cmp_ge_f32_e64 s[4:5], 0, v55
	v_add_u32_e32 v55, 1, v45
	s_nop 0
	v_cndmask_b32_e64 v54, v45, v54, s[4:5]
	v_fma_f32 v45, -v55, v45, v44
	v_cmp_lt_f32_e64 s[4:5], 0, v45
	s_nop 1
	v_cndmask_b32_e64 v45, v54, v55, s[4:5]
	v_mul_f32_e32 v54, 0x37800000, v45
	v_cndmask_b32_e32 v45, v45, v54, vcc
	v_cmp_class_f32_e32 vcc, v44, v83
	s_nop 1
	v_cndmask_b32_e32 v44, v45, v44, vcc
	v_div_scale_f32 v45, s[4:5], v44, v44, 1.0
	v_rcp_f32_e32 v54, v45
	s_min_i32 s4, s22, 0x4000
	s_and_b32 s8, s4, 0x3ffff000
	s_lshl_b64 s[4:5], s[22:23], 12
	v_fma_f32 v55, -v45, v54, 1.0
	v_fmac_f32_e32 v54, v55, v54
	v_div_scale_f32 v55, vcc, 1.0, v44, 1.0
	v_mul_f32_e32 v56, v55, v54
	v_fma_f32 v57, -v45, v56, v55
	v_fmac_f32_e32 v56, v57, v54
	v_fma_f32 v45, -v45, v56, v55
	v_div_fmas_f32 v45, v45, v54, v56
	v_div_fixup_f32 v44, v45, v44, 1.0
	v_lshl_add_u32 v45, s8, 2, v77
	ds_read_b128 v[54:57], v45 offset:8192
	ds_read_b128 v[58:61], v45
	v_pk_mul_f32 v[100:101], v[84:85], v[44:45] op_sel_hi:[1,0]
	v_pk_mul_f32 v[62:63], v[62:63], v[44:45] op_sel_hi:[1,0]
	ds_read_b128 v[84:87], v45 offset:9216
	ds_read_b128 v[88:91], v45 offset:1024
	s_waitcnt lgkmcnt(3)
	v_pk_add_f32 v[54:55], v[54:55], 1.0 op_sel_hi:[1,0]
	v_pk_add_f32 v[56:57], v[56:57], 1.0 op_sel_hi:[1,0]
	s_waitcnt lgkmcnt(2)
	v_pk_fma_f32 v[54:55], v[54:55], v[100:101], v[58:59]
	v_pk_fma_f32 v[56:57], v[56:57], v[62:63], v[60:61]
	v_cvt_pk_bf16_f32 v58, v54, v55
	v_cvt_pk_bf16_f32 v59, v56, v57
	v_lshl_add_u64 v[54:55], v[68:69], 0, s[4:5]
	v_pk_mul_f32 v[56:57], v[94:95], v[44:45] op_sel_hi:[1,0]
	s_waitcnt lgkmcnt(1)
	v_pk_add_f32 v[62:63], v[84:85], 1.0 op_sel_hi:[1,0]
	global_store_dwordx2 v[54:55], v[58:59], off
	v_pk_mul_f32 v[58:59], v[92:93], v[44:45] op_sel_hi:[1,0]
	v_pk_add_f32 v[60:61], v[86:87], 1.0 op_sel_hi:[1,0]
	s_waitcnt lgkmcnt(0)
	v_pk_fma_f32 v[56:57], v[62:63], v[56:57], v[88:89]
	v_pk_fma_f32 v[58:59], v[60:61], v[58:59], v[90:91]
	v_cvt_pk_bf16_f32 v56, v56, v57
	v_cvt_pk_bf16_f32 v57, v58, v59
	global_store_dwordx2 v[54:55], v[56:57], off offset:512
	ds_read_b128 v[56:59], v45 offset:10240
	ds_read_b128 v[60:63], v45 offset:2048
	v_pk_mul_f32 v[88:89], v[96:97], v[44:45] op_sel_hi:[1,0]
	v_pk_mul_f32 v[90:91], v[98:99], v[44:45] op_sel_hi:[1,0]
	ds_read_b128 v[84:87], v45 offset:11264
	s_waitcnt lgkmcnt(2)
	v_pk_add_f32 v[94:95], v[56:57], 1.0 op_sel_hi:[1,0]
	v_pk_add_f32 v[92:93], v[58:59], 1.0 op_sel_hi:[1,0]
	s_waitcnt lgkmcnt(1)
	v_pk_fma_f32 v[60:61], v[94:95], v[88:89], v[60:61]
	ds_read_b128 v[56:59], v45 offset:3072
	v_bfe_u32 v88, v60, 16, 1
	v_add3_u32 v60, v60, v88, s28
	v_bfe_u32 v88, v61, 16, 1
	v_pk_fma_f32 v[62:63], v[92:93], v[90:91], v[62:63]
	v_lshrrev_b32_e32 v60, 16, v60
	v_add3_u32 v61, v61, v88, s28
	v_and_or_b32 v60, v61, s29, v60
	v_cvt_pk_bf16_f32 v61, v62, v63
	v_pk_mul_f32 v[50:51], v[50:51], v[44:45] op_sel_hi:[1,0]
	s_waitcnt lgkmcnt(1)
	v_pk_add_f32 v[62:63], v[84:85], 1.0 op_sel_hi:[1,0]
	global_store_dwordx2 v[54:55], v[60:61], off offset:1024
	s_waitcnt lgkmcnt(0)
	v_pk_fma_f32 v[50:51], v[62:63], v[50:51], v[56:57]
	v_pk_mul_f32 v[52:53], v[52:53], v[44:45] op_sel_hi:[1,0]
	v_pk_add_f32 v[60:61], v[86:87], 1.0 op_sel_hi:[1,0]
	v_pk_fma_f32 v[52:53], v[60:61], v[52:53], v[58:59]
	v_cvt_pk_bf16_f32 v50, v50, v51
	v_cvt_pk_bf16_f32 v51, v52, v53
	global_store_dwordx2 v[54:55], v[50:51], off offset:1536
	ds_read_b128 v[50:53], v45 offset:12288
	ds_read_b128 v[56:59], v45 offset:4096
	v_pk_mul_f32 v[60:61], v[48:49], v[44:45] op_sel_hi:[1,0]
	v_pk_mul_f32 v[62:63], v[46:47], v[44:45] op_sel_hi:[1,0]
	ds_read_b128 v[46:49], v45 offset:13312
	s_waitcnt lgkmcnt(2)
	v_pk_add_f32 v[84:85], v[52:53], 1.0 op_sel_hi:[1,0]
	v_pk_add_f32 v[86:87], v[50:51], 1.0 op_sel_hi:[1,0]
	ds_read_b128 v[50:53], v45 offset:5120
	v_pk_mul_f32 v[40:41], v[40:41], v[44:45] op_sel_hi:[1,0]
	s_waitcnt lgkmcnt(1)
	v_pk_add_f32 v[46:47], v[46:47], 1.0 op_sel_hi:[1,0]
	v_pk_fma_f32 v[56:57], v[86:87], v[60:61], v[56:57]
	v_pk_mul_f32 v[42:43], v[42:43], v[44:45] op_sel_hi:[1,0]
	s_waitcnt lgkmcnt(0)
	v_pk_fma_f32 v[40:41], v[46:47], v[40:41], v[50:51]
	v_pk_add_f32 v[48:49], v[48:49], 1.0 op_sel_hi:[1,0]
	v_pk_fma_f32 v[58:59], v[84:85], v[62:63], v[58:59]
	v_pk_fma_f32 v[42:43], v[48:49], v[42:43], v[52:53]
	v_cvt_pk_bf16_f32 v56, v56, v57
	v_cvt_pk_bf16_f32 v40, v40, v41
	v_cvt_pk_bf16_f32 v57, v58, v59
	v_cvt_pk_bf16_f32 v41, v42, v43
	global_store_dwordx2 v[54:55], v[56:57], off offset:2048
	global_store_dwordx2 v[54:55], v[40:41], off offset:2560
	ds_read_b128 v[40:43], v45 offset:14336
	ds_read_b128 v[46:49], v45 offset:6144
	v_pk_mul_f32 v[50:51], v[36:37], v[44:45] op_sel_hi:[1,0]
	v_pk_mul_f32 v[52:53], v[38:39], v[44:45] op_sel_hi:[1,0]
	ds_read_b128 v[36:39], v45 offset:15360
	s_waitcnt lgkmcnt(2)
	v_pk_add_f32 v[58:59], v[40:41], 1.0 op_sel_hi:[1,0]
	v_pk_add_f32 v[56:57], v[42:43], 1.0 op_sel_hi:[1,0]
	s_waitcnt lgkmcnt(1)
	v_pk_fma_f32 v[46:47], v[58:59], v[50:51], v[46:47]
	ds_read_b128 v[40:43], v45 offset:7168
	v_pk_fma_f32 v[48:49], v[56:57], v[52:53], v[48:49]
	v_cvt_pk_bf16_f32 v46, v46, v47
	v_bfe_u32 v45, v48, 16, 1
	v_add3_u32 v45, v48, v45, s28
	v_lshrrev_b32_e32 v45, 16, v45
	v_pk_mul_f32 v[34:35], v[34:35], v[44:45] op_sel_hi:[1,0]
	s_waitcnt lgkmcnt(1)
	v_pk_add_f32 v[36:37], v[36:37], 1.0 op_sel_hi:[1,0]
	v_pk_mul_f32 v[32:33], v[32:33], v[44:45] op_sel_hi:[1,0]
	s_waitcnt lgkmcnt(0)
	v_pk_fma_f32 v[34:35], v[36:37], v[34:35], v[40:41]
	v_pk_add_f32 v[38:39], v[38:39], 1.0 op_sel_hi:[1,0]
	v_pk_fma_f32 v[32:33], v[38:39], v[32:33], v[42:43]
	v_cvt_pk_bf16_f32 v34, v34, v35
	v_bfe_u32 v47, v49, 16, 1
	v_add3_u32 v47, v49, v47, s28
	v_and_or_b32 v47, v47, s29, v45
	v_cvt_pk_bf16_f32 v35, v32, v33
	global_store_dwordx2 v[54:55], v[46:47], off offset:3072
	global_store_dwordx2 v[54:55], v[34:35], off offset:3584
	s_branch .LBB0_197

.LBB0_916:
	s_mov_b64 s[0:1], s[78:79]
	s_waitcnt lgkmcnt(0)
	s_barrier
	v_mbcnt_lo_u32_b32 v0, -1, 0
	v_mbcnt_hi_u32_b32 v0, -1, v0
	v_writelane_b32 v255, s54, 9
	v_add_u32_e32 v64, s66, v0
	s_load_dwordx2 s[6:7], s[0:1], 0xd0
	s_load_dwordx4 s[16:19], s[0:1], 0x80
	v_writelane_b32 v255, s55, 10
	v_readlane_b32 s36, v253, 56
	v_readlane_b32 s4, v255, 5
	s_lshl_b32 s8, s4, 11
	s_mov_b32 s9, s36
	s_lshl_b64 s[64:65], s[8:9], 2
	s_waitcnt lgkmcnt(0)
	s_add_u32 s8, s16, s64
	v_lshlrev_b32_e32 v0, 2, v64
	s_addc_u32 s9, s17, s65
	v_ashrrev_i32_e32 v1, 31, v0
	s_add_u32 s14, s18, s64
	v_lshlrev_b64 v[10:11], 2, v[0:1]
	s_addc_u32 s15, s19, s65
	v_lshl_add_u64 v[2:3], s[8:9], 0, v[10:11]
	global_load_dwordx4 v[2:5], v[2:3], off
	v_lshl_add_u64 v[6:7], s[14:15], 0, v[10:11]
	global_load_dwordx4 v[6:9], v[6:7], off
	v_readlane_b32 s50, v254, 6
	v_readlane_b32 s51, v254, 7
	s_mul_i32 s8, s4, 0xf000
	s_mov_b32 s9, s36
	s_lshl_b64 s[50:51], s[8:9], 2
	s_add_u32 s8, s6, s50
	s_addc_u32 s9, s7, s51
	v_lshl_add_u32 v1, v64, 4, 0
	v_lshl_add_u64 v[46:47], s[8:9], 0, v[10:11]
	s_mov_b32 s8, 0x104000
	v_readlane_b32 s5, v255, 6
	v_readlane_b32 s37, v253, 57
	v_readlane_b32 s38, v253, 58
	v_readlane_b32 s39, v253, 59
	v_readlane_b32 s40, v253, 60
	v_readlane_b32 s41, v253, 61
	v_readlane_b32 s42, v253, 62
	v_readlane_b32 s43, v253, 63
	v_readlane_b32 s44, v254, 0
	v_readlane_b32 s45, v254, 1
	v_readlane_b32 s46, v254, 2
	v_readlane_b32 s47, v254, 3
	v_readlane_b32 s48, v254, 4
	v_readlane_b32 s49, v254, 5
	s_waitcnt vmcnt(0)
	ds_write_b128 v1, v[2:5]
	ds_write_b128 v1, v[6:9] offset:8192
	v_add_co_u32_e32 v2, vcc, s8, v46
	s_mov_b32 s8, 0x106000
	s_nop 0
	v_addc_co_u32_e32 v3, vcc, 0, v47, vcc
	v_add_co_u32_e32 v6, vcc, s8, v46
	s_mov_b32 s8, 0x108000
	s_nop 0
	v_addc_co_u32_e32 v7, vcc, 0, v47, vcc
	v_add_co_u32_e32 v10, vcc, s8, v46
	s_mov_b32 s8, 0x110000
	s_nop 0
	v_addc_co_u32_e32 v11, vcc, 0, v47, vcc
	v_add_co_u32_e32 v14, vcc, s8, v46
	s_mov_b32 s8, 0x112000
	s_nop 0
	v_addc_co_u32_e32 v15, vcc, 0, v47, vcc
	v_add_co_u32_e32 v18, vcc, s8, v46
	s_mov_b32 s8, 0x114000
	s_nop 0
	v_addc_co_u32_e32 v19, vcc, 0, v47, vcc
	v_add_co_u32_e32 v22, vcc, s8, v46
	s_mov_b32 s8, 0x11c000
	s_nop 0
	v_addc_co_u32_e32 v23, vcc, 0, v47, vcc
	v_add_co_u32_e32 v26, vcc, s8, v46
	s_mov_b32 s8, 0x11e000
	s_nop 0
	v_addc_co_u32_e32 v27, vcc, 0, v47, vcc
	v_add_co_u32_e32 v30, vcc, s8, v46
	s_mov_b32 s8, 0x120000
	s_nop 0
	v_addc_co_u32_e32 v31, vcc, 0, v47, vcc
	v_add_co_u32_e32 v34, vcc, s8, v46
	s_mov_b32 s8, 0x128000
	s_nop 0
	v_addc_co_u32_e32 v35, vcc, 0, v47, vcc
	v_add_co_u32_e32 v38, vcc, s8, v46
	global_load_dwordx4 v[2:5], v[2:3], off
	s_nop 0
	v_addc_co_u32_e32 v39, vcc, 0, v47, vcc
	s_mov_b32 s8, 0x12a000
	global_load_dwordx4 v[6:9], v[6:7], off
	v_add_co_u32_e32 v42, vcc, s8, v46
	global_load_dwordx4 v[26:29], v[26:27], off
	s_nop 0
	v_addc_co_u32_e32 v43, vcc, 0, v47, vcc
	global_load_dwordx4 v[10:13], v[10:11], off
	s_mov_b32 s8, 0x12c000
	global_load_dwordx4 v[30:33], v[30:31], off
	v_add_co_u32_e32 v46, vcc, s8, v46
	global_load_dwordx4 v[14:17], v[14:15], off
	s_nop 0
	v_addc_co_u32_e32 v47, vcc, 0, v47, vcc
	global_load_dwordx4 v[34:37], v[34:35], off
	v_readlane_b32 s8, v253, 34
	global_load_dwordx4 v[18:21], v[18:19], off
	v_readlane_b32 s9, v253, 35
	global_load_dwordx4 v[38:41], v[38:39], off
	s_andn2_b64 vcc, exec, s[8:9]
	global_load_dwordx4 v[22:25], v[22:23], off
	s_nop 0
	global_load_dwordx4 v[42:45], v[42:43], off
	s_nop 0
	global_load_dwordx4 v[46:49], v[46:47], off
	s_waitcnt vmcnt(11)
	ds_write_b128 v1, v[2:5] offset:16384
	s_waitcnt vmcnt(10)
	ds_write_b128 v1, v[6:9] offset:24576
	s_waitcnt vmcnt(8)
	ds_write_b128 v1, v[10:13] offset:32768
	s_waitcnt vmcnt(6)
	ds_write_b128 v1, v[14:17] offset:40960
	s_waitcnt vmcnt(4)
	ds_write_b128 v1, v[18:21] offset:49152
	s_waitcnt vmcnt(2)
	ds_write_b128 v1, v[22:25] offset:57344
	v_add_u32_e32 v2, 0x10000, v1
	ds_write_b128 v2, v[26:29]
	v_add_u32_e32 v2, 0x12000, v1
	ds_write_b128 v2, v[30:33]
	v_add_u32_e32 v2, 0x14000, v1
	ds_write_b128 v2, v[34:37]
	v_add_u32_e32 v2, 0x16000, v1
	ds_write_b128 v2, v[38:41]
	v_add_u32_e32 v2, 0x18000, v1
	v_add_u32_e32 v1, 0x1a000, v1
	s_waitcnt vmcnt(0)
	ds_write_b128 v1, v[46:49]
	v_cndmask_b32_e64 v1, 0, 1, s[8:9]
	v_cmp_ne_u32_e64 s[4:5], 1, v1
	ds_write_b128 v2, v[42:45]
	s_waitcnt lgkmcnt(0)
	s_nop 1
	v_writelane_b32 v255, s4, 41
	s_barrier
	s_nop 0
	v_writelane_b32 v255, s5, 42
	s_cbranch_vccnz .LBB0_923
	v_and_b32_e32 v65, 0xfc, v0
	v_bfrev_b32_e32 v1, 0.5
	s_movk_i32 s4, 0x80
	v_lshl_add_u32 v176, v65, 2, 0
	v_bitop3_b32 v170, v0, 4, v1 bitop3:0x6c
	v_bitop3_b32 v171, v0, 8, v1 bitop3:0x6c
	v_bitop3_b32 v172, v0, 16, v1 bitop3:0x6c
	v_bitop3_b32 v173, v0, 32, v1 bitop3:0x6c
	v_bitop3_b32 v174, v0, 64, v1 bitop3:0x6c
	v_bitop3_b32 v175, v0, s4, v1 bitop3:0x6c
	ds_read_b128 v[0:3], v176
	ds_read_b128 v[4:7], v176 offset:1024
	ds_read_b128 v[8:11], v176 offset:8192
	ds_read_b128 v[12:15], v176 offset:9216
	ds_read_b128 v[16:19], v176 offset:2048
	ds_read_b128 v[20:23], v176 offset:3072
	ds_read_b128 v[24:27], v176 offset:10240
	ds_read_b128 v[28:31], v176 offset:11264
	ds_read_b128 v[32:35], v176 offset:4096
	ds_read_b128 v[36:39], v176 offset:5120
	ds_read_b128 v[40:43], v176 offset:12288
	ds_read_b128 v[44:47], v176 offset:13312
	ds_read_b128 v[48:51], v176 offset:6144
	ds_read_b128 v[52:55], v176 offset:7168
	ds_read_b128 v[56:59], v176 offset:14336
	ds_read_b128 v[60:63], v176 offset:15360
	v_lshlrev_b32_e32 v144, 1, v65
	v_lshl_add_u64 v[66:67], s[6:7], 0, v[144:145]
	s_mov_b64 s[4:5], 0x19400000
	v_lshl_add_u64 v[128:129], v[66:67], 0, s[4:5]
	s_mov_b64 s[4:5], 0x15000000
	v_lshl_add_u64 v[132:133], v[66:67], 0, s[4:5]
	v_readlane_b32 s4, v254, 24
	s_add_u32 s6, s6, s4
	v_readlane_b32 s4, v254, 27
	v_and_b32_e32 v64, 63, v64
	s_addc_u32 s7, s7, s4
	v_lshlrev_b32_e32 v144, 3, v64
	s_mov_b64 s[14:15], 0xc800000
	v_lshl_add_u64 v[134:135], s[6:7], 0, v[144:145]
	v_readlane_b32 s6, v254, 28
	s_mov_b32 s8, 0xf7800000
	s_mov_b32 s10, 0xf7800200
	s_mov_b32 s12, 0xf7800400
	s_mov_b32 s20, 0xf7800600
	s_mov_b32 s22, 0xf7800800
	s_mov_b32 s24, 0xf7800a00
	s_mov_b32 s26, 0xf7800c00
	s_mov_b32 s28, 0xf7800e00
	v_lshl_add_u64 v[130:131], v[66:67], 0, s[14:15]
	s_mov_b32 s18, s6
	s_mov_b32 s4, 0xffff0000
	s_mov_b32 s5, 0xf800000
	s_mov_b32 s9, -1
	s_mov_b32 s11, -1
	s_mov_b32 s13, -1
	s_mov_b32 s21, -1
	s_mov_b32 s23, -1
	s_mov_b32 s25, -1
	s_mov_b32 s27, -1
	s_mov_b32 s29, -1
	s_mov_b32 s30, 0x3fb504f3
	v_readlane_b32 s7, v254, 29
	s_branch .LBB0_919

.LBB0_921:
	s_waitcnt vmcnt(15)
	v_cvt_f32_f16_sdwa v181, v166 dst_sel:DWORD dst_unused:UNUSED_PAD src0_sel:WORD_1
	v_cvt_f32_f16_e32 v180, v166
	s_waitcnt vmcnt(14)
	v_lshlrev_b32_e32 v178, 16, v168
	v_and_b32_e32 v179, 0xffff0000, v168
	v_lshlrev_b32_e32 v168, 16, v169
	v_and_b32_e32 v169, 0xffff0000, v169
	v_cvt_f32_f16_sdwa v183, v167 dst_sel:DWORD dst_unused:UNUSED_PAD src0_sel:WORD_1
	v_cvt_f32_f16_e32 v182, v167
	s_waitcnt lgkmcnt(7)
	v_pk_mul_f32 v[166:167], v[124:125], v[178:179]
	v_pk_mul_f32 v[124:125], v[126:127], v[168:169]
	s_waitcnt vmcnt(10)
	v_cvt_f32_f16_sdwa v169, v164 dst_sel:DWORD dst_unused:UNUSED_PAD src0_sel:WORD_1
	v_cvt_f32_f16_e32 v168, v164
	v_pk_fma_f32 v[126:127], v[180:181], s[30:31], v[166:167] op_sel_hi:[1,0,1]
	v_lshlrev_b32_e32 v166, 16, v162
	v_and_b32_e32 v167, 0xffff0000, v162
	v_lshlrev_b32_e32 v162, 16, v163
	v_and_b32_e32 v163, 0xffff0000, v163
	v_cvt_f32_f16_sdwa v179, v165 dst_sel:DWORD dst_unused:UNUSED_PAD src0_sel:WORD_1
	v_cvt_f32_f16_e32 v178, v165
	s_waitcnt lgkmcnt(6)
	v_pk_mul_f32 v[164:165], v[120:121], v[166:167]
	v_pk_mul_f32 v[120:121], v[122:123], v[162:163]
	v_pk_fma_f32 v[122:123], v[168:169], s[30:31], v[164:165] op_sel_hi:[1,0,1]
	s_waitcnt vmcnt(9)
	v_cvt_f32_f16_sdwa v165, v160 dst_sel:DWORD dst_unused:UNUSED_PAD src0_sel:WORD_1
	v_cvt_f32_f16_e32 v164, v160
	v_lshlrev_b32_e32 v162, 16, v158
	v_and_b32_e32 v163, 0xffff0000, v158
	v_lshlrev_b32_e32 v158, 16, v159
	v_and_b32_e32 v159, 0xffff0000, v159
	v_cvt_f32_f16_sdwa v167, v161 dst_sel:DWORD dst_unused:UNUSED_PAD src0_sel:WORD_1
	v_cvt_f32_f16_e32 v166, v161
	s_waitcnt lgkmcnt(5)
	v_pk_mul_f32 v[160:161], v[116:117], v[162:163]
	v_pk_mul_f32 v[116:117], v[118:119], v[158:159]
	v_pk_fma_f32 v[118:119], v[164:165], s[30:31], v[160:161] op_sel_hi:[1,0,1]
	s_waitcnt vmcnt(8)
	v_cvt_f32_f16_sdwa v161, v154 dst_sel:DWORD dst_unused:UNUSED_PAD src0_sel:WORD_1
	v_cvt_f32_f16_e32 v160, v154
	v_lshlrev_b32_e32 v158, 16, v156
	v_and_b32_e32 v159, 0xffff0000, v156
	v_lshlrev_b32_e32 v156, 16, v157
	v_and_b32_e32 v157, 0xffff0000, v157
	v_cvt_f32_f16_sdwa v163, v155 dst_sel:DWORD dst_unused:UNUSED_PAD src0_sel:WORD_1
	v_cvt_f32_f16_e32 v162, v155
	s_waitcnt lgkmcnt(4)
	v_pk_mul_f32 v[154:155], v[112:113], v[158:159]
	v_pk_mul_f32 v[112:113], v[114:115], v[156:157]
	v_pk_fma_f32 v[114:115], v[160:161], s[30:31], v[154:155] op_sel_hi:[1,0,1]
	s_waitcnt vmcnt(6)
	v_lshlrev_b32_e32 v154, 16, v152
	v_and_b32_e32 v155, 0xffff0000, v152
	v_lshlrev_b32_e32 v152, 16, v153
	v_and_b32_e32 v153, 0xffff0000, v153
	s_waitcnt lgkmcnt(3)
	v_pk_mul_f32 v[110:111], v[110:111], v[152:153]
	s_waitcnt vmcnt(2)
	v_cvt_f32_f16_sdwa v153, v148 dst_sel:DWORD dst_unused:UNUSED_PAD src0_sel:WORD_1
	v_cvt_f32_f16_e32 v152, v148
	v_cvt_f32_f16_sdwa v157, v150 dst_sel:DWORD dst_unused:UNUSED_PAD src0_sel:WORD_1
	v_cvt_f32_f16_sdwa v159, v151 dst_sel:DWORD dst_unused:UNUSED_PAD src0_sel:WORD_1
	v_cvt_f32_f16_e32 v158, v151
	v_cvt_f32_f16_e32 v156, v150
	v_lshlrev_b32_e32 v150, 16, v146
	v_and_b32_e32 v151, 0xffff0000, v146
	v_pk_mul_f32 v[108:109], v[108:109], v[154:155]
	v_lshlrev_b32_e32 v146, 16, v147
	v_and_b32_e32 v147, 0xffff0000, v147
	v_cvt_f32_f16_sdwa v155, v149 dst_sel:DWORD dst_unused:UNUSED_PAD src0_sel:WORD_1
	v_cvt_f32_f16_e32 v154, v149
	s_waitcnt lgkmcnt(2)
	v_pk_mul_f32 v[148:149], v[104:105], v[150:151]
	v_pk_mul_f32 v[104:105], v[106:107], v[146:147]
	v_pk_fma_f32 v[106:107], v[152:153], s[30:31], v[148:149] op_sel_hi:[1,0,1]
	s_waitcnt vmcnt(1)
	v_cvt_f32_f16_sdwa v149, v142 dst_sel:DWORD dst_unused:UNUSED_PAD src0_sel:WORD_1
	v_cvt_f32_f16_e32 v148, v142
	v_lshlrev_b32_e32 v146, 16, v140
	v_and_b32_e32 v147, 0xffff0000, v140
	v_lshlrev_b32_e32 v140, 16, v141
	v_and_b32_e32 v141, 0xffff0000, v141
	v_cvt_f32_f16_sdwa v151, v143 dst_sel:DWORD dst_unused:UNUSED_PAD src0_sel:WORD_1
	v_cvt_f32_f16_e32 v150, v143
	s_waitcnt lgkmcnt(1)
	v_pk_mul_f32 v[142:143], v[100:101], v[146:147]
	v_pk_mul_f32 v[100:101], v[102:103], v[140:141]
	v_lshlrev_b32_e32 v140, 16, v138
	v_and_b32_e32 v141, 0xffff0000, v138
	v_lshlrev_b32_e32 v138, 16, v139
	v_and_b32_e32 v139, 0xffff0000, v139
	v_pk_fma_f32 v[124:125], v[182:183], s[30:31], v[124:125] op_sel_hi:[1,0,1]
	v_pk_fma_f32 v[120:121], v[178:179], s[30:31], v[120:121] op_sel_hi:[1,0,1]
	v_pk_fma_f32 v[102:103], v[148:149], s[30:31], v[142:143] op_sel_hi:[1,0,1]
	s_waitcnt vmcnt(0)
	v_cvt_f32_f16_sdwa v143, v136 dst_sel:DWORD dst_unused:UNUSED_PAD src0_sel:WORD_1
	v_cvt_f32_f16_sdwa v147, v137 dst_sel:DWORD dst_unused:UNUSED_PAD src0_sel:WORD_1
	v_cvt_f32_f16_e32 v146, v137
	v_cvt_f32_f16_e32 v142, v136
	s_waitcnt lgkmcnt(0)
	v_pk_mul_f32 v[98:99], v[98:99], v[138:139]
	v_mov_b32_e32 v136, v126
	v_mov_b32_e32 v137, v122
	v_mov_b32_e32 v138, v127
	v_mov_b32_e32 v139, v123
	v_pk_mul_f32 v[96:97], v[96:97], v[140:141]
	v_pk_add_f32 v[136:137], v[136:137], v[138:139]
	v_mov_b32_e32 v138, v124
	v_mov_b32_e32 v139, v120
	v_mov_b32_e32 v140, v125
	v_mov_b32_e32 v141, v121
	v_pk_fma_f32 v[116:117], v[166:167], s[30:31], v[116:117] op_sel_hi:[1,0,1]
	v_pk_add_f32 v[138:139], v[138:139], v[140:141]
	v_mov_b32_e32 v140, v118
	v_pk_add_f32 v[136:137], v[136:137], v[138:139]
	v_pk_mov_b32 v[138:139], v[118:119], v[116:117] op_sel:[1,0]
	v_mov_b32_e32 v141, v117
	v_pk_add_f32 v[138:139], v[138:139], v[140:141]
	v_pk_fma_f32 v[112:113], v[162:163], s[30:31], v[112:113] op_sel_hi:[1,0,1]
	v_pk_fma_f32 v[110:111], v[158:159], s[30:31], v[110:111] op_sel_hi:[1,0,1]
	v_pk_fma_f32 v[108:109], v[156:157], s[30:31], v[108:109] op_sel_hi:[1,0,1]
	v_add_f32_e32 v136, 0, v136
	v_pk_add_f32 v[138:139], v[138:139], v[138:139] op_sel:[0,1] op_sel_hi:[1,0]
	v_pk_fma_f32 v[96:97], v[142:143], s[30:31], v[96:97] op_sel_hi:[1,0,1]
	v_add_f32_e32 v136, v136, v137
	v_add_f32_e32 v140, v114, v115
	v_add_f32_e32 v142, v112, v113
	v_mov_b32_e32 v137, v108
	v_mov_b32_e32 v139, v109
	v_mov_b32_e32 v141, v110
	v_mov_b32_e32 v143, v111
	v_pk_fma_f32 v[104:105], v[154:155], s[30:31], v[104:105] op_sel_hi:[1,0,1]
	v_pk_add_f32 v[136:137], v[136:137], v[138:139]
	v_pk_add_f32 v[138:139], v[140:141], v[142:143]
	v_mov_b32_e32 v140, v106
	v_pk_add_f32 v[136:137], v[136:137], v[138:139]
	v_pk_mov_b32 v[138:139], v[106:107], v[104:105] op_sel:[1,0]
	v_mov_b32_e32 v141, v105
	v_pk_add_f32 v[138:139], v[138:139], v[140:141]
	v_pk_fma_f32 v[100:101], v[150:151], s[30:31], v[100:101] op_sel_hi:[1,0,1]
	v_pk_fma_f32 v[98:99], v[146:147], s[30:31], v[98:99] op_sel_hi:[1,0,1]
	v_pk_add_f32 v[136:137], v[136:137], v[136:137] op_sel:[0,1] op_sel_hi:[1,0]
	v_pk_add_f32 v[138:139], v[138:139], v[138:139] op_sel:[0,1] op_sel_hi:[1,0]
	v_add_f32_e32 v140, v102, v103
	v_add_f32_e32 v142, v100, v101
	v_mov_b32_e32 v137, v96
	v_mov_b32_e32 v139, v97
	v_mov_b32_e32 v141, v98
	v_mov_b32_e32 v143, v99
	v_pk_add_f32 v[136:137], v[136:137], v[138:139]
	v_pk_add_f32 v[138:139], v[140:141], v[142:143]
	v_lshl_add_u64 v[164:165], v[134:135], 0, s[24:25]
	v_pk_add_f32 v[136:137], v[136:137], v[138:139]
	v_lshl_add_u64 v[168:169], v[134:135], 0, s[28:29]
	v_add_f32_e32 v136, v136, v137
	ds_bpermute_b32 v137, v170, v136
	s_waitcnt lgkmcnt(0)
	v_add_f32_e32 v136, v136, v137
	ds_bpermute_b32 v137, v171, v136
	s_waitcnt lgkmcnt(0)
	v_add_f32_e32 v136, v136, v137
	ds_bpermute_b32 v137, v172, v136
	s_waitcnt lgkmcnt(0)
	v_add_f32_e32 v136, v136, v137
	ds_bpermute_b32 v137, v173, v136
	s_waitcnt lgkmcnt(0)
	v_add_f32_e32 v136, v136, v137
	ds_bpermute_b32 v137, v174, v136
	s_waitcnt lgkmcnt(0)
	v_add_f32_e32 v136, v136, v137
	ds_bpermute_b32 v137, v175, v136
	s_waitcnt lgkmcnt(0)
	v_add_f32_e32 v146, v136, v137
	v_fmamk_f32 v127, v146, 0xba000000, v127
	v_fmamk_f32 v123, v146, 0xba000000, v123
	v_fmamk_f32 v125, v146, 0xba000000, v125
	v_fmac_f32_e32 v126, 0xba000000, v146
	v_fmamk_f32 v121, v146, 0xba000000, v121
	v_fmac_f32_e32 v122, 0xba000000, v146
	v_mov_b32_e32 v138, v127
	v_mov_b32_e32 v139, v123
	v_fmac_f32_e32 v124, 0xba000000, v146
	v_fmac_f32_e32 v120, 0xba000000, v146
	v_mov_b32_e32 v136, v126
	v_mov_b32_e32 v137, v122
	v_pk_mul_f32 v[138:139], v[138:139], v[138:139]
	v_mov_b32_e32 v140, v125
	v_mov_b32_e32 v141, v121
	v_pk_fma_f32 v[136:137], v[136:137], v[136:137], v[138:139]
	v_mov_b32_e32 v138, v124
	v_mov_b32_e32 v139, v120
	v_pk_mul_f32 v[140:141], v[140:141], v[140:141]
	v_fmamk_f32 v119, v146, 0xba000000, v119
	v_pk_fma_f32 v[138:139], v[138:139], v[138:139], v[140:141]
	v_fmac_f32_e32 v118, 0xba000000, v146
	v_pk_add_f32 v[136:137], v[136:137], v[138:139]
	v_fmamk_f32 v117, v146, 0xba000000, v117
	v_fmac_f32_e32 v116, 0xba000000, v146
	v_pk_add_f32 v[136:137], v[136:137], v[136:137] op_sel_hi:[0,1]
	v_pk_mul_f32 v[138:139], v[116:117], v[116:117]
	v_pk_mul_f32 v[140:141], v[118:119], v[118:119]
	v_fmac_f32_e32 v114, 0xba000000, v146
	v_pk_mov_b32 v[142:143], v[140:141], v[138:139] op_sel:[1,0]
	v_mov_b32_e32 v141, v139
	v_fmamk_f32 v115, v146, 0xba000000, v115
	v_fmac_f32_e32 v112, 0xba000000, v146
	v_mul_f32_e32 v136, v114, v114
	v_pk_add_f32 v[138:139], v[142:143], v[140:141]
	v_fmamk_f32 v113, v146, 0xba000000, v113
	v_pk_fma_f32 v[140:141], v[114:115], v[114:115], v[136:137] op_sel_hi:[1,1,0]
	v_mul_f32_e32 v136, v112, v112
	v_pk_add_f32 v[138:139], v[138:139], v[138:139] op_sel_hi:[0,1]
	v_pk_fma_f32 v[142:143], v[112:113], v[112:113], v[136:137] op_sel_hi:[1,1,0]
	v_fmamk_f32 v111, v146, 0xba000000, v111
	v_fmac_f32_e32 v110, 0xba000000, v146
	v_fmamk_f32 v109, v146, 0xba000000, v109
	v_fmac_f32_e32 v108, 0xba000000, v146
	v_mul_f32_e32 v140, v108, v108
	v_mul_f32_e32 v142, v109, v109
	v_mul_f32_e32 v138, v110, v110
	v_mul_f32_e32 v136, v111, v111
	v_pk_add_f32 v[140:141], v[140:141], v[142:143]
	v_pk_add_f32 v[136:137], v[138:139], v[136:137]
	v_fmamk_f32 v107, v146, 0xba000000, v107
	v_pk_add_f32 v[136:137], v[140:141], v[136:137]
	v_fmac_f32_e32 v106, 0xba000000, v146
	v_fmamk_f32 v105, v146, 0xba000000, v105
	v_fmac_f32_e32 v104, 0xba000000, v146
	v_pk_add_f32 v[136:137], v[136:137], v[136:137] op_sel_hi:[0,1]
	v_pk_mul_f32 v[138:139], v[104:105], v[104:105]
	v_pk_mul_f32 v[140:141], v[106:107], v[106:107]
	v_fmac_f32_e32 v102, 0xba000000, v146
	v_pk_mov_b32 v[142:143], v[140:141], v[138:139] op_sel:[1,0]
	v_mov_b32_e32 v141, v139
	v_fmamk_f32 v103, v146, 0xba000000, v103
	v_fmac_f32_e32 v100, 0xba000000, v146
	v_mul_f32_e32 v136, v102, v102
	v_pk_add_f32 v[138:139], v[142:143], v[140:141]
	v_fmamk_f32 v101, v146, 0xba000000, v101
	v_pk_fma_f32 v[140:141], v[102:103], v[102:103], v[136:137] op_sel_hi:[1,1,0]
	v_mul_f32_e32 v136, v100, v100
	v_pk_add_f32 v[138:139], v[138:139], v[138:139] op_sel_hi:[0,1]
	v_pk_fma_f32 v[142:143], v[100:101], v[100:101], v[136:137] op_sel_hi:[1,1,0]
	v_fmamk_f32 v99, v146, 0xba000000, v99
	v_fmac_f32_e32 v98, 0xba000000, v146
	v_fmamk_f32 v97, v146, 0xba000000, v97
	v_fmac_f32_e32 v96, 0xba000000, v146
	v_mul_f32_e32 v140, v96, v96
	v_mul_f32_e32 v142, v97, v97
	v_mul_f32_e32 v138, v98, v98
	v_mul_f32_e32 v136, v99, v99
	v_pk_add_f32 v[140:141], v[140:141], v[142:143]
	v_pk_add_f32 v[136:137], v[138:139], v[136:137]
	s_nop 0
	v_pk_add_f32 v[136:137], v[140:141], v[136:137]
	s_nop 0
	v_add_f32_e32 v136, v136, v137
	ds_bpermute_b32 v137, v170, v136
	s_waitcnt lgkmcnt(0)
	v_add_f32_e32 v136, v136, v137
	ds_bpermute_b32 v137, v171, v136
	s_waitcnt lgkmcnt(0)
	v_add_f32_e32 v136, v136, v137
	ds_bpermute_b32 v137, v172, v136
	s_waitcnt lgkmcnt(0)
	v_add_f32_e32 v136, v136, v137
	ds_bpermute_b32 v137, v173, v136
	s_waitcnt lgkmcnt(0)
	v_add_f32_e32 v136, v136, v137
	ds_bpermute_b32 v137, v174, v136
	s_waitcnt lgkmcnt(0)
	v_add_f32_e32 v136, v136, v137
	ds_bpermute_b32 v137, v175, v136
	s_waitcnt lgkmcnt(0)
	v_add_f32_e32 v136, v136, v137
	v_fmamk_f32 v136, v136, 0x3a000000, v229
	v_mul_f32_e32 v137, 0x4f800000, v136
	v_cmp_gt_f32_e32 vcc, s5, v136
	s_nop 1
	v_cndmask_b32_e32 v136, v136, v137, vcc
	v_sqrt_f32_e32 v137, v136
	s_nop 0
	v_add_u32_e32 v138, -1, v137
	v_fma_f32 v139, -v138, v137, v136
	v_cmp_ge_f32_e64 s[6:7], 0, v139
	v_add_u32_e32 v139, 1, v137
	s_nop 0
	v_cndmask_b32_e64 v138, v137, v138, s[6:7]
	v_fma_f32 v137, -v139, v137, v136
	v_cmp_lt_f32_e64 s[6:7], 0, v137
	s_nop 1
	v_cndmask_b32_e64 v137, v138, v139, s[6:7]
	v_mul_f32_e32 v138, 0x37800000, v137
	v_cndmask_b32_e32 v137, v137, v138, vcc
	v_cmp_class_f32_e32 vcc, v136, v230
	s_nop 1
	v_cndmask_b32_e32 v136, v137, v136, vcc
	v_div_scale_f32 v137, s[6:7], v136, v136, 1.0
	v_rcp_f32_e32 v138, v137
	s_nop 0
	v_fma_f32 v139, -v137, v138, 1.0
	v_fmac_f32_e32 v138, v139, v138
	v_div_scale_f32 v139, vcc, 1.0, v136, 1.0
	v_mul_f32_e32 v140, v139, v138
	v_fma_f32 v141, -v137, v140, v139
	v_fmac_f32_e32 v140, v141, v138
	v_fma_f32 v137, -v137, v140, v139
	v_div_fmas_f32 v137, v137, v138, v140
	v_div_fixup_f32 v136, v137, v136, 1.0
	v_pk_mul_f32 v[138:139], v[124:125], v[136:137] op_sel_hi:[1,0]
	v_pk_mul_f32 v[124:125], v[126:127], v[136:137] op_sel_hi:[1,0]
	v_pk_fma_f32 v[126:127], v[2:3], v[138:139], v[10:11]
	v_pk_mul_f32 v[138:139], v[120:121], v[136:137] op_sel_hi:[1,0]
	v_pk_mul_f32 v[120:121], v[122:123], v[136:137] op_sel_hi:[1,0]
	v_pk_fma_f32 v[122:123], v[6:7], v[138:139], v[14:15]
	v_pk_mul_f32 v[138:139], v[116:117], v[136:137] op_sel_hi:[1,0]
	v_pk_mul_f32 v[116:117], v[118:119], v[136:137] op_sel_hi:[1,0]
	v_pk_fma_f32 v[118:119], v[18:19], v[138:139], v[26:27]
	v_pk_mul_f32 v[138:139], v[112:113], v[136:137] op_sel_hi:[1,0]
	v_pk_mul_f32 v[112:113], v[114:115], v[136:137] op_sel_hi:[1,0]
	v_pk_fma_f32 v[114:115], v[22:23], v[138:139], v[30:31]
	v_pk_mul_f32 v[138:139], v[104:105], v[136:137] op_sel_hi:[1,0]
	v_pk_fma_f32 v[124:125], v[0:1], v[124:125], v[8:9]
	v_pk_fma_f32 v[120:121], v[4:5], v[120:121], v[12:13]
	v_pk_mul_f32 v[104:105], v[106:107], v[136:137] op_sel_hi:[1,0]
	v_pk_fma_f32 v[106:107], v[38:39], v[138:139], v[46:47]
	v_pk_mul_f32 v[138:139], v[100:101], v[136:137] op_sel_hi:[1,0]
	v_pk_mul_f32 v[110:111], v[110:111], v[136:137] op_sel_hi:[1,0]
	v_pk_mul_f32 v[108:109], v[108:109], v[136:137] op_sel_hi:[1,0]
	v_pk_mul_f32 v[100:101], v[102:103], v[136:137] op_sel_hi:[1,0]
	v_pk_fma_f32 v[102:103], v[50:51], v[138:139], v[58:59]
	v_pk_mul_f32 v[98:99], v[98:99], v[136:137] op_sel_hi:[1,0]
	v_pk_mul_f32 v[96:97], v[96:97], v[136:137] op_sel_hi:[1,0]
	v_mov_b32_e32 v136, v120
	v_mov_b32_e32 v137, v124
	v_mov_b32_e32 v138, v121
	v_mov_b32_e32 v139, v125
	v_pk_add_f32 v[136:137], v[136:137], v[138:139]
	v_mov_b32_e32 v138, v122
	v_mov_b32_e32 v139, v126
	v_mov_b32_e32 v140, v123
	v_mov_b32_e32 v141, v127
	v_pk_fma_f32 v[116:117], v[16:17], v[116:117], v[24:25]
	v_pk_add_f32 v[138:139], v[138:139], v[140:141]
	v_mov_b32_e32 v140, v116
	v_pk_add_f32 v[136:137], v[136:137], v[138:139]
	v_pk_mov_b32 v[138:139], v[116:117], v[118:119] op_sel:[1,0]
	v_mov_b32_e32 v141, v119
	v_pk_add_f32 v[138:139], v[138:139], v[140:141]
	v_pk_fma_f32 v[112:113], v[20:21], v[112:113], v[28:29]
	v_pk_fma_f32 v[108:109], v[32:33], v[108:109], v[40:41]
	v_pk_fma_f32 v[110:111], v[34:35], v[110:111], v[42:43]
	v_add_f32_e32 v137, 0, v137
	v_pk_add_f32 v[138:139], v[138:139], v[138:139] op_sel_hi:[0,1]
	v_add_f32_e32 v137, v136, v137
	v_add_f32_e32 v141, v112, v113
	v_add_f32_e32 v143, v114, v115
	v_mov_b32_e32 v140, v108
	v_mov_b32_e32 v142, v109
	v_mov_b32_e32 v138, v110
	v_mov_b32_e32 v136, v111
	v_pk_fma_f32 v[104:105], v[36:37], v[104:105], v[44:45]
	v_pk_add_f32 v[140:141], v[140:141], v[142:143]
	v_pk_add_f32 v[136:137], v[138:139], v[136:137]
	v_pk_mov_b32 v[138:139], v[104:105], v[106:107] op_sel:[1,0]
	v_pk_add_f32 v[136:137], v[140:141], v[136:137]
	v_mov_b32_e32 v140, v104
	v_mov_b32_e32 v141, v107
	v_pk_add_f32 v[138:139], v[138:139], v[140:141]
	v_pk_fma_f32 v[100:101], v[48:49], v[100:101], v[56:57]
	v_pk_fma_f32 v[96:97], v[52:53], v[96:97], v[60:61]
	v_pk_fma_f32 v[98:99], v[54:55], v[98:99], v[62:63]
	v_pk_add_f32 v[136:137], v[136:137], v[136:137] op_sel_hi:[0,1]
	v_pk_add_f32 v[138:139], v[138:139], v[138:139] op_sel_hi:[0,1]
	v_add_f32_e32 v141, v100, v101
	v_add_f32_e32 v143, v102, v103
	v_mov_b32_e32 v140, v96
	v_mov_b32_e32 v142, v97
	v_mov_b32_e32 v138, v98
	v_mov_b32_e32 v136, v99
	v_pk_add_f32 v[140:141], v[140:141], v[142:143]
	v_pk_add_f32 v[136:137], v[138:139], v[136:137]
	v_cvt_pk_f16_f32 v138, v120, v121
	v_pk_add_f32 v[136:137], v[140:141], v[136:137]
	v_cvt_pk_f16_f32 v139, v122, v123
	v_add_f32_e32 v136, v136, v137
	ds_bpermute_b32 v137, v170, v136
	v_cvt_pk_f16_f32 v142, v112, v113
	v_cvt_pk_f16_f32 v143, v114, v115
	v_cvt_pk_f16_f32 v149, v106, v107
	v_cvt_pk_f16_f32 v148, v104, v105
	s_waitcnt lgkmcnt(0)
	v_add_f32_e32 v136, v136, v137
	ds_bpermute_b32 v137, v171, v136
	v_cvt_pk_f16_f32 v153, v98, v99
	v_cvt_pk_f16_f32 v152, v96, v97
	s_waitcnt lgkmcnt(0)
	v_add_f32_e32 v140, v136, v137
	ds_bpermute_b32 v141, v172, v140
	v_cvt_pk_f16_f32 v136, v124, v125
	v_cvt_pk_f16_f32 v137, v126, v127
	s_waitcnt lgkmcnt(0)
	v_add_f32_e32 v146, v140, v141
	ds_bpermute_b32 v147, v173, v146
	v_cvt_pk_f16_f32 v141, v118, v119
	v_cvt_pk_f16_f32 v140, v116, v117
	s_waitcnt lgkmcnt(0)
	v_add_f32_e32 v150, v146, v147
	ds_bpermute_b32 v151, v174, v150
	v_cvt_pk_f16_f32 v147, v110, v111
	v_cvt_pk_f16_f32 v146, v108, v109
	s_waitcnt lgkmcnt(0)
	v_add_f32_e32 v154, v150, v151
	ds_bpermute_b32 v155, v175, v154
	v_cvt_pk_f16_f32 v150, v100, v101
	v_cvt_pk_f16_f32 v151, v102, v103
	s_waitcnt lgkmcnt(0)
	v_add_f32_e32 v162, v154, v155
	v_fmamk_f32 v125, v162, 0xba000000, v125
	v_fmamk_f32 v121, v162, 0xba000000, v121
	v_fmamk_f32 v127, v162, 0xba000000, v127
	v_fmac_f32_e32 v124, 0xba000000, v162
	v_fmamk_f32 v123, v162, 0xba000000, v123
	v_fmac_f32_e32 v120, 0xba000000, v162
	v_mov_b32_e32 v156, v125
	v_mov_b32_e32 v157, v121
	v_fmac_f32_e32 v126, 0xba000000, v162
	v_fmac_f32_e32 v122, 0xba000000, v162
	v_mov_b32_e32 v154, v124
	v_mov_b32_e32 v155, v120
	v_pk_mul_f32 v[156:157], v[156:157], v[156:157]
	v_mov_b32_e32 v158, v127
	v_mov_b32_e32 v159, v123
	v_pk_fma_f32 v[154:155], v[154:155], v[154:155], v[156:157]
	v_mov_b32_e32 v156, v126
	v_mov_b32_e32 v157, v122
	v_pk_mul_f32 v[158:159], v[158:159], v[158:159]
	v_fmamk_f32 v117, v162, 0xba000000, v117
	v_pk_fma_f32 v[156:157], v[156:157], v[156:157], v[158:159]
	v_fmac_f32_e32 v116, 0xba000000, v162
	v_pk_add_f32 v[154:155], v[154:155], v[156:157]
	v_fmamk_f32 v119, v162, 0xba000000, v119
	v_fmac_f32_e32 v118, 0xba000000, v162
	v_pk_add_f32 v[154:155], v[154:155], v[154:155] op_sel_hi:[0,1]
	v_pk_mul_f32 v[156:157], v[118:119], v[118:119]
	v_pk_mul_f32 v[158:159], v[116:117], v[116:117]
	v_fmac_f32_e32 v112, 0xba000000, v162
	v_pk_mov_b32 v[160:161], v[158:159], v[156:157] op_sel:[1,0]
	v_mov_b32_e32 v159, v157
	v_fmamk_f32 v113, v162, 0xba000000, v113
	v_fmac_f32_e32 v114, 0xba000000, v162
	v_mul_f32_e32 v154, v112, v112
	v_pk_add_f32 v[156:157], v[160:161], v[158:159]
	v_fmamk_f32 v115, v162, 0xba000000, v115
	v_pk_fma_f32 v[158:159], v[112:113], v[112:113], v[154:155] op_sel_hi:[1,1,0]
	v_mul_f32_e32 v154, v114, v114
	v_pk_add_f32 v[156:157], v[156:157], v[156:157] op_sel_hi:[0,1]
	v_pk_fma_f32 v[160:161], v[114:115], v[114:115], v[154:155] op_sel_hi:[1,1,0]
	v_fmamk_f32 v111, v162, 0xba000000, v111
	v_fmac_f32_e32 v110, 0xba000000, v162
	v_fmamk_f32 v109, v162, 0xba000000, v109
	v_fmac_f32_e32 v108, 0xba000000, v162
	v_mul_f32_e32 v158, v108, v108
	v_mul_f32_e32 v160, v109, v109
	v_mul_f32_e32 v156, v110, v110
	v_mul_f32_e32 v154, v111, v111
	v_pk_add_f32 v[158:159], v[158:159], v[160:161]
	v_pk_add_f32 v[154:155], v[156:157], v[154:155]
	v_fmamk_f32 v105, v162, 0xba000000, v105
	v_pk_add_f32 v[154:155], v[158:159], v[154:155]
	v_fmac_f32_e32 v104, 0xba000000, v162
	v_fmamk_f32 v107, v162, 0xba000000, v107
	v_fmac_f32_e32 v106, 0xba000000, v162
	v_pk_add_f32 v[154:155], v[154:155], v[154:155] op_sel_hi:[0,1]
	v_pk_mul_f32 v[156:157], v[106:107], v[106:107]
	v_pk_mul_f32 v[158:159], v[104:105], v[104:105]
	v_fmac_f32_e32 v100, 0xba000000, v162
	v_pk_mov_b32 v[160:161], v[158:159], v[156:157] op_sel:[1,0]
	v_mov_b32_e32 v159, v157
	v_fmamk_f32 v101, v162, 0xba000000, v101
	v_fmac_f32_e32 v102, 0xba000000, v162
	v_mul_f32_e32 v154, v100, v100
	v_pk_add_f32 v[156:157], v[160:161], v[158:159]
	v_fmamk_f32 v103, v162, 0xba000000, v103
	v_pk_fma_f32 v[158:159], v[100:101], v[100:101], v[154:155] op_sel_hi:[1,1,0]
	v_mul_f32_e32 v154, v102, v102
	v_pk_add_f32 v[156:157], v[156:157], v[156:157] op_sel_hi:[0,1]
	v_pk_fma_f32 v[160:161], v[102:103], v[102:103], v[154:155] op_sel_hi:[1,1,0]
	v_fmamk_f32 v99, v162, 0xba000000, v99
	v_fmac_f32_e32 v98, 0xba000000, v162
	v_fmamk_f32 v97, v162, 0xba000000, v97
	v_fmac_f32_e32 v96, 0xba000000, v162
	v_mul_f32_e32 v158, v96, v96
	v_mul_f32_e32 v160, v97, v97
	v_mul_f32_e32 v156, v98, v98
	v_mul_f32_e32 v154, v99, v99
	v_pk_add_f32 v[158:159], v[158:159], v[160:161]
	v_pk_add_f32 v[154:155], v[156:157], v[154:155]
	v_lshl_add_u64 v[156:157], v[134:135], 0, s[10:11]
	v_pk_add_f32 v[154:155], v[158:159], v[154:155]
	v_lshl_add_u64 v[160:161], v[134:135], 0, s[20:21]
	v_add_f32_e32 v154, v154, v155
	ds_bpermute_b32 v155, v170, v154
	v_lshl_add_u64 v[162:163], v[134:135], 0, s[22:23]
	s_waitcnt lgkmcnt(0)
	v_add_f32_e32 v154, v154, v155
	ds_bpermute_b32 v155, v171, v154
	s_waitcnt lgkmcnt(0)
	v_add_f32_e32 v154, v154, v155
	ds_bpermute_b32 v155, v172, v154
	s_waitcnt lgkmcnt(0)
	v_add_f32_e32 v158, v154, v155
	ds_bpermute_b32 v159, v173, v158
	v_lshl_add_u64 v[154:155], v[134:135], 0, s[8:9]
	global_store_dwordx2 v[154:155], v[136:137], off
	global_store_dwordx2 v[156:157], v[138:139], off
	s_waitcnt lgkmcnt(0)
	v_add_f32_e32 v166, v158, v159
	ds_bpermute_b32 v167, v174, v166
	v_lshl_add_u64 v[158:159], v[134:135], 0, s[12:13]
	global_store_dwordx2 v[158:159], v[140:141], off
	global_store_dwordx2 v[160:161], v[142:143], off
	global_store_dwordx2 v[162:163], v[146:147], off
	s_waitcnt lgkmcnt(0)
	v_add_f32_e32 v177, v166, v167
	ds_bpermute_b32 v178, v175, v177
	v_lshl_add_u64 v[166:167], v[134:135], 0, s[26:27]
	global_store_dwordx2 v[164:165], v[148:149], off
	global_store_dwordx2 v[166:167], v[150:151], off
	global_store_dwordx2 v[168:169], v[152:153], off
	s_waitcnt lgkmcnt(0)
	v_add_f32_e32 v136, v177, v178
	v_fmamk_f32 v136, v136, 0x3a000000, v229
	v_mul_f32_e32 v137, 0x4f800000, v136
	v_cmp_gt_f32_e32 vcc, s5, v136
	s_nop 1
	v_cndmask_b32_e32 v136, v136, v137, vcc
	v_sqrt_f32_e32 v137, v136
	s_nop 0
	v_add_u32_e32 v138, -1, v137
	v_fma_f32 v139, -v138, v137, v136
	v_cmp_ge_f32_e64 s[6:7], 0, v139
	v_add_u32_e32 v139, 1, v137
	s_nop 0
	v_cndmask_b32_e64 v138, v137, v138, s[6:7]
	v_fma_f32 v137, -v139, v137, v136
	v_cmp_lt_f32_e64 s[6:7], 0, v137
	s_nop 1
	v_cndmask_b32_e64 v137, v138, v139, s[6:7]
	v_mul_f32_e32 v138, 0x37800000, v137
	v_cndmask_b32_e32 v137, v137, v138, vcc
	v_cmp_class_f32_e32 vcc, v136, v230
	s_nop 1
	v_cndmask_b32_e32 v136, v137, v136, vcc
	v_div_scale_f32 v137, s[6:7], v136, v136, 1.0
	v_rcp_f32_e32 v138, v137
	s_nop 0
	v_fma_f32 v139, -v137, v138, 1.0
	v_fmac_f32_e32 v138, v139, v138
	v_div_scale_f32 v139, vcc, 1.0, v136, 1.0
	v_mul_f32_e32 v140, v139, v138
	v_fma_f32 v141, -v137, v140, v139
	v_fmac_f32_e32 v140, v141, v138
	v_fma_f32 v137, -v137, v140, v139
	v_div_fmas_f32 v137, v137, v138, v140
	ds_read_b128 v[138:141], v144 offset:32768
	ds_read_b128 v[146:149], v144 offset:24576
	v_div_fixup_f32 v136, v137, v136, 1.0
	v_pk_mul_f32 v[142:143], v[124:125], v[136:137] op_sel_hi:[1,0]
	v_pk_mul_f32 v[150:151], v[126:127], v[136:137] op_sel_hi:[1,0]
	s_waitcnt lgkmcnt(1)
	v_pk_add_f32 v[154:155], v[138:139], 1.0 op_sel_hi:[1,0]
	ds_read_b128 v[124:127], v144 offset:33792
	s_waitcnt lgkmcnt(1)
	v_pk_fma_f32 v[142:143], v[154:155], v[142:143], v[146:147]
	v_pk_add_f32 v[152:153], v[140:141], 1.0 op_sel_hi:[1,0]
	ds_read_b128 v[138:141], v144 offset:25600
	v_pk_fma_f32 v[148:149], v[152:153], v[150:151], v[148:149]
	v_cvt_pk_bf16_f32 v142, v142, v143
	v_bfe_u32 v137, v148, 16, 1
	v_add3_u32 v137, v148, v137, s69
	v_lshrrev_b32_e32 v137, 16, v137
	v_pk_mul_f32 v[120:121], v[120:121], v[136:137] op_sel_hi:[1,0]
	s_waitcnt lgkmcnt(1)
	v_pk_add_f32 v[124:125], v[124:125], 1.0 op_sel_hi:[1,0]
	v_pk_mul_f32 v[122:123], v[122:123], v[136:137] op_sel_hi:[1,0]
	s_waitcnt lgkmcnt(0)
	v_pk_fma_f32 v[120:121], v[124:125], v[120:121], v[138:139]
	v_pk_add_f32 v[126:127], v[126:127], 1.0 op_sel_hi:[1,0]
	v_pk_fma_f32 v[122:123], v[126:127], v[122:123], v[140:141]
	v_cvt_pk_bf16_f32 v120, v120, v121
	v_bfe_u32 v143, v149, 16, 1
	v_add3_u32 v143, v149, v143, s69
	v_and_or_b32 v143, v143, s4, v137
	v_cvt_pk_bf16_f32 v121, v122, v123
	global_store_dwordx2 v[134:135], v[142:143], off
	global_store_dwordx2 v[134:135], v[120:121], off offset:512
	ds_read_b128 v[120:123], v144 offset:34816
	ds_read_b128 v[124:127], v144 offset:26624
	v_pk_mul_f32 v[138:139], v[116:117], v[136:137] op_sel_hi:[1,0]
	v_pk_mul_f32 v[140:141], v[118:119], v[136:137] op_sel_hi:[1,0]
	ds_read_b128 v[116:119], v144 offset:35840
	s_waitcnt lgkmcnt(2)
	v_pk_add_f32 v[142:143], v[122:123], 1.0 op_sel_hi:[1,0]
	v_pk_add_f32 v[146:147], v[120:121], 1.0 op_sel_hi:[1,0]
	ds_read_b128 v[120:123], v144 offset:27648
	s_waitcnt lgkmcnt(2)
	v_pk_fma_f32 v[124:125], v[146:147], v[138:139], v[124:125]
	s_waitcnt lgkmcnt(1)
	v_pk_add_f32 v[116:117], v[116:117], 1.0 op_sel_hi:[1,0]
	v_bfe_u32 v137, v124, 16, 1
	v_add3_u32 v124, v124, v137, s69
	v_bfe_u32 v137, v125, 16, 1
	v_pk_mul_f32 v[112:113], v[112:113], v[136:137] op_sel_hi:[1,0]
	v_pk_mul_f32 v[114:115], v[114:115], v[136:137] op_sel_hi:[1,0]
	s_waitcnt lgkmcnt(0)
	v_pk_fma_f32 v[112:113], v[116:117], v[112:113], v[120:121]
	v_pk_add_f32 v[118:119], v[118:119], 1.0 op_sel_hi:[1,0]
	v_pk_fma_f32 v[126:127], v[142:143], v[140:141], v[126:127]
	v_lshrrev_b32_e32 v124, 16, v124
	v_add3_u32 v125, v125, v137, s69
	v_pk_fma_f32 v[114:115], v[118:119], v[114:115], v[122:123]
	v_and_or_b32 v124, v125, s4, v124
	v_cvt_pk_bf16_f32 v112, v112, v113
	v_cvt_pk_bf16_f32 v125, v126, v127
	v_cvt_pk_bf16_f32 v113, v114, v115
	global_store_dwordx2 v[134:135], v[124:125], off offset:1024
	global_store_dwordx2 v[134:135], v[112:113], off offset:1536
	ds_read_b128 v[112:115], v144 offset:36864
	ds_read_b128 v[116:119], v144 offset:28672
	v_pk_mul_f32 v[120:121], v[108:109], v[136:137] op_sel_hi:[1,0]
	v_pk_mul_f32 v[122:123], v[110:111], v[136:137] op_sel_hi:[1,0]
	ds_read_b128 v[108:111], v144 offset:37888
	s_waitcnt lgkmcnt(2)
	v_pk_add_f32 v[124:125], v[114:115], 1.0 op_sel_hi:[1,0]
	v_pk_add_f32 v[126:127], v[112:113], 1.0 op_sel_hi:[1,0]
	ds_read_b128 v[112:115], v144 offset:29696
	v_pk_mul_f32 v[104:105], v[104:105], v[136:137] op_sel_hi:[1,0]
	s_waitcnt lgkmcnt(1)
	v_pk_add_f32 v[108:109], v[108:109], 1.0 op_sel_hi:[1,0]
	v_pk_fma_f32 v[116:117], v[126:127], v[120:121], v[116:117]
	v_pk_mul_f32 v[106:107], v[106:107], v[136:137] op_sel_hi:[1,0]
	s_waitcnt lgkmcnt(0)
	v_pk_fma_f32 v[104:105], v[108:109], v[104:105], v[112:113]
	v_pk_add_f32 v[110:111], v[110:111], 1.0 op_sel_hi:[1,0]
	v_pk_fma_f32 v[118:119], v[124:125], v[122:123], v[118:119]
	v_pk_fma_f32 v[106:107], v[110:111], v[106:107], v[114:115]
	v_cvt_pk_bf16_f32 v116, v116, v117
	v_cvt_pk_bf16_f32 v104, v104, v105
	v_cvt_pk_bf16_f32 v117, v118, v119
	v_cvt_pk_bf16_f32 v105, v106, v107
	global_store_dwordx2 v[134:135], v[116:117], off offset:2048
	global_store_dwordx2 v[134:135], v[104:105], off offset:2560
	ds_read_b128 v[104:107], v144 offset:38912
	ds_read_b128 v[108:111], v144 offset:30720
	v_pk_mul_f32 v[112:113], v[100:101], v[136:137] op_sel_hi:[1,0]
	v_pk_mul_f32 v[114:115], v[102:103], v[136:137] op_sel_hi:[1,0]
	ds_read_b128 v[100:103], v144 offset:39936
	s_waitcnt lgkmcnt(2)
	v_pk_add_f32 v[116:117], v[106:107], 1.0 op_sel_hi:[1,0]
	v_pk_add_f32 v[118:119], v[104:105], 1.0 op_sel_hi:[1,0]
	ds_read_b128 v[104:107], v144 offset:31744
	v_pk_mul_f32 v[96:97], v[96:97], v[136:137] op_sel_hi:[1,0]
	s_waitcnt lgkmcnt(1)
	v_pk_add_f32 v[100:101], v[100:101], 1.0 op_sel_hi:[1,0]
	v_pk_fma_f32 v[108:109], v[118:119], v[112:113], v[108:109]
	v_pk_mul_f32 v[98:99], v[98:99], v[136:137] op_sel_hi:[1,0]
	s_waitcnt lgkmcnt(0)
	v_pk_fma_f32 v[96:97], v[100:101], v[96:97], v[104:105]
	v_pk_add_f32 v[102:103], v[102:103], 1.0 op_sel_hi:[1,0]
	v_pk_fma_f32 v[110:111], v[116:117], v[114:115], v[110:111]
	v_pk_fma_f32 v[98:99], v[102:103], v[98:99], v[106:107]
	v_cvt_pk_bf16_f32 v108, v108, v109
	v_cvt_pk_bf16_f32 v96, v96, v97
	v_cvt_pk_bf16_f32 v109, v110, v111
	v_cvt_pk_bf16_f32 v97, v98, v99
	s_andn2_b64 vcc, exec, s[16:17]
	global_store_dwordx2 v[134:135], v[108:109], off offset:3072
	global_store_dwordx2 v[134:135], v[96:97], off offset:3584
	s_cbranch_vccnz .LBB0_918
	v_mov_b32_e32 v96, v68
	v_mov_b32_e32 v97, v64
	v_mov_b32_e32 v98, v69
	v_mov_b32_e32 v99, v65
	v_pk_add_f32 v[96:97], v[96:97], v[98:99]
	v_mov_b32_e32 v98, v70
	v_mov_b32_e32 v99, v66
	v_mov_b32_e32 v100, v71
	v_mov_b32_e32 v101, v67
	v_pk_add_f32 v[98:99], v[98:99], v[100:101]
	v_mov_b32_e32 v100, v72
	v_pk_add_f32 v[96:97], v[96:97], v[98:99]
	v_mov_b32_e32 v98, v73
	v_mov_b32_e32 v99, v74
	v_mov_b32_e32 v101, v75
	v_pk_add_f32 v[98:99], v[98:99], v[100:101]
	v_add_f32_e32 v97, 0, v97
	v_pk_add_f32 v[98:99], v[98:99], v[98:99] op_sel_hi:[0,1]
	v_add_f32_e32 v97, v96, v97
	v_add_f32_e32 v101, v76, v77
	v_add_f32_e32 v103, v78, v79
	v_mov_b32_e32 v100, v80
	v_mov_b32_e32 v102, v81
	v_mov_b32_e32 v98, v82
	v_mov_b32_e32 v96, v83
	v_pk_add_f32 v[100:101], v[100:101], v[102:103]
	v_pk_add_f32 v[96:97], v[98:99], v[96:97]
	v_mov_b32_e32 v98, v85
	v_pk_add_f32 v[96:97], v[100:101], v[96:97]
	v_mov_b32_e32 v99, v86
	v_mov_b32_e32 v100, v84
	v_mov_b32_e32 v101, v87
	v_pk_add_f32 v[98:99], v[98:99], v[100:101]
	v_pk_add_f32 v[96:97], v[96:97], v[96:97] op_sel_hi:[0,1]
	v_pk_add_f32 v[98:99], v[98:99], v[98:99] op_sel_hi:[0,1]
	v_add_f32_e32 v101, v88, v89
	v_add_f32_e32 v103, v90, v91
	v_mov_b32_e32 v100, v92
	v_mov_b32_e32 v102, v93
	v_mov_b32_e32 v98, v94
	v_mov_b32_e32 v96, v95
	v_pk_add_f32 v[100:101], v[100:101], v[102:103]
	v_pk_add_f32 v[96:97], v[98:99], v[96:97]
	s_ashr_i32 s15, s14, 31
	v_pk_add_f32 v[96:97], v[100:101], v[96:97]
	s_lshl_b64 s[16:17], s[14:15], 12
	v_add_f32_e32 v96, v96, v97
	ds_bpermute_b32 v97, v170, v96
	s_lshr_b32 s14, s14, 12
	s_mulk_i32 s14, 0x6000
	s_waitcnt lgkmcnt(0)
	v_add_f32_e32 v96, v96, v97
	ds_bpermute_b32 v97, v171, v96
	s_waitcnt lgkmcnt(0)
	v_add_f32_e32 v96, v96, v97
	ds_bpermute_b32 v97, v172, v96
	s_waitcnt lgkmcnt(0)
	v_add_f32_e32 v96, v96, v97
	ds_bpermute_b32 v97, v173, v96
	s_waitcnt lgkmcnt(0)
	v_add_f32_e32 v96, v96, v97
	ds_bpermute_b32 v97, v174, v96
	s_waitcnt lgkmcnt(0)
	v_add_f32_e32 v96, v96, v97
	ds_bpermute_b32 v97, v175, v96
	s_waitcnt lgkmcnt(0)
	v_add_f32_e32 v104, v96, v97
	v_fmamk_f32 v65, v104, 0xba000000, v65
	v_fmamk_f32 v69, v104, 0xba000000, v69
	v_fmamk_f32 v67, v104, 0xba000000, v67
	v_fmac_f32_e32 v64, 0xba000000, v104
	v_fmamk_f32 v71, v104, 0xba000000, v71
	v_fmac_f32_e32 v68, 0xba000000, v104
	v_mov_b32_e32 v98, v65
	v_mov_b32_e32 v99, v69
	v_fmamk_f32 v66, v104, 0xba000000, v66
	v_fmamk_f32 v70, v104, 0xba000000, v70
	v_mov_b32_e32 v96, v64
	v_mov_b32_e32 v97, v68
	v_pk_mul_f32 v[98:99], v[98:99], v[98:99]
	v_mov_b32_e32 v100, v67
	v_mov_b32_e32 v101, v71
	v_pk_fma_f32 v[96:97], v[96:97], v[96:97], v[98:99]
	v_mov_b32_e32 v98, v66
	v_mov_b32_e32 v99, v70
	v_pk_mul_f32 v[100:101], v[100:101], v[100:101]
	v_fmamk_f32 v73, v104, 0xba000000, v73
	v_pk_fma_f32 v[98:99], v[98:99], v[98:99], v[100:101]
	v_fmamk_f32 v72, v104, 0xba000000, v72
	v_pk_add_f32 v[96:97], v[96:97], v[98:99]
	v_fmamk_f32 v75, v104, 0xba000000, v75
	v_fmac_f32_e32 v74, 0xba000000, v104
	v_pk_add_f32 v[96:97], v[96:97], v[96:97] op_sel_hi:[0,1]
	v_pk_mul_f32 v[98:99], v[74:75], v[74:75]
	v_pk_mul_f32 v[100:101], v[72:73], v[72:73]
	v_fmamk_f32 v76, v104, 0xba000000, v76
	v_pk_mov_b32 v[102:103], v[100:101], v[98:99] op_sel:[1,0]
	v_mov_b32_e32 v101, v99
	v_fmamk_f32 v77, v104, 0xba000000, v77
	v_fmac_f32_e32 v78, 0xba000000, v104
	v_mul_f32_e32 v96, v76, v76
	v_pk_add_f32 v[98:99], v[102:103], v[100:101]
	v_fmamk_f32 v79, v104, 0xba000000, v79
	v_pk_fma_f32 v[100:101], v[76:77], v[76:77], v[96:97] op_sel_hi:[1,1,0]
	v_mul_f32_e32 v96, v78, v78
	v_pk_add_f32 v[98:99], v[98:99], v[98:99] op_sel_hi:[0,1]
	v_pk_fma_f32 v[102:103], v[78:79], v[78:79], v[96:97] op_sel_hi:[1,1,0]
	v_fmamk_f32 v83, v104, 0xba000000, v83
	v_fmamk_f32 v82, v104, 0xba000000, v82
	v_fmamk_f32 v81, v104, 0xba000000, v81
	v_fmac_f32_e32 v80, 0xba000000, v104
	v_mul_f32_e32 v100, v80, v80
	v_mul_f32_e32 v102, v81, v81
	v_mul_f32_e32 v98, v82, v82
	v_mul_f32_e32 v96, v83, v83
	v_pk_add_f32 v[100:101], v[100:101], v[102:103]
	v_pk_add_f32 v[96:97], v[98:99], v[96:97]
	v_fmamk_f32 v85, v104, 0xba000000, v85
	v_pk_add_f32 v[96:97], v[100:101], v[96:97]
	v_fmamk_f32 v84, v104, 0xba000000, v84
	v_fmamk_f32 v87, v104, 0xba000000, v87
	v_fmac_f32_e32 v86, 0xba000000, v104
	v_pk_add_f32 v[96:97], v[96:97], v[96:97] op_sel_hi:[0,1]
	v_pk_mul_f32 v[98:99], v[86:87], v[86:87]
	v_pk_mul_f32 v[100:101], v[84:85], v[84:85]
	v_fmamk_f32 v88, v104, 0xba000000, v88
	v_pk_mov_b32 v[102:103], v[100:101], v[98:99] op_sel:[1,0]
	v_mov_b32_e32 v101, v99
	v_fmamk_f32 v89, v104, 0xba000000, v89
	v_fmac_f32_e32 v90, 0xba000000, v104
	v_mul_f32_e32 v96, v88, v88
	v_pk_add_f32 v[98:99], v[102:103], v[100:101]
	v_fmamk_f32 v91, v104, 0xba000000, v91
	v_pk_fma_f32 v[100:101], v[88:89], v[88:89], v[96:97] op_sel_hi:[1,1,0]
	v_mul_f32_e32 v96, v90, v90
	v_pk_add_f32 v[98:99], v[98:99], v[98:99] op_sel_hi:[0,1]
	v_pk_fma_f32 v[102:103], v[90:91], v[90:91], v[96:97] op_sel_hi:[1,1,0]
	v_fmamk_f32 v95, v104, 0xba000000, v95
	v_fmamk_f32 v94, v104, 0xba000000, v94
	v_fmamk_f32 v93, v104, 0xba000000, v93
	v_fmac_f32_e32 v92, 0xba000000, v104
	v_mul_f32_e32 v100, v92, v92
	v_mul_f32_e32 v102, v93, v93
	v_mul_f32_e32 v98, v94, v94
	v_mul_f32_e32 v96, v95, v95
	v_pk_add_f32 v[100:101], v[100:101], v[102:103]
	v_pk_add_f32 v[96:97], v[98:99], v[96:97]
	s_nop 0
	v_pk_add_f32 v[96:97], v[100:101], v[96:97]
	s_nop 0
	v_add_f32_e32 v96, v96, v97
	ds_bpermute_b32 v97, v170, v96
	s_waitcnt lgkmcnt(0)
	v_add_f32_e32 v96, v96, v97
	ds_bpermute_b32 v97, v171, v96
	s_waitcnt lgkmcnt(0)
	v_add_f32_e32 v96, v96, v97
	ds_bpermute_b32 v97, v172, v96
	s_waitcnt lgkmcnt(0)
	v_add_f32_e32 v96, v96, v97
	ds_bpermute_b32 v97, v173, v96
	s_waitcnt lgkmcnt(0)
	v_add_f32_e32 v96, v96, v97
	ds_bpermute_b32 v97, v174, v96
	s_waitcnt lgkmcnt(0)
	v_add_f32_e32 v96, v96, v97
	ds_bpermute_b32 v97, v175, v96
	s_waitcnt lgkmcnt(0)
	v_add_f32_e32 v96, v96, v97
	v_fmamk_f32 v96, v96, 0x3a000000, v229
	v_cmp_gt_f32_e32 vcc, s5, v96
	v_mul_f32_e32 v97, 0x4f800000, v96
	s_nop 0
	v_cndmask_b32_e32 v96, v96, v97, vcc
	v_sqrt_f32_e32 v97, v96
	s_nop 0
	v_add_u32_e32 v98, -1, v97
	v_fma_f32 v99, -v98, v97, v96
	v_cmp_ge_f32_e64 s[6:7], 0, v99
	v_add_u32_e32 v99, 1, v97
	s_nop 0
	v_cndmask_b32_e64 v98, v97, v98, s[6:7]
	v_fma_f32 v97, -v99, v97, v96
	v_cmp_lt_f32_e64 s[6:7], 0, v97
	s_nop 1
	v_cndmask_b32_e64 v97, v98, v99, s[6:7]
	v_mul_f32_e32 v98, 0x37800000, v97
	v_cndmask_b32_e32 v97, v97, v98, vcc
	v_cmp_class_f32_e32 vcc, v96, v230
	s_nop 1
	v_cndmask_b32_e32 v96, v97, v96, vcc
	v_div_scale_f32 v97, s[6:7], v96, v96, 1.0
	v_rcp_f32_e32 v98, v97
	s_nop 0
	v_fma_f32 v99, -v97, v98, 1.0
	v_fmac_f32_e32 v98, v99, v98
	v_div_scale_f32 v99, vcc, 1.0, v96, 1.0
	v_mul_f32_e32 v100, v99, v98
	v_fma_f32 v101, -v97, v100, v99
	v_fmac_f32_e32 v100, v101, v98
	v_fma_f32 v97, -v97, v100, v99
	v_div_fmas_f32 v97, v97, v98, v100
	v_div_fixup_f32 v96, v97, v96, 1.0
	v_pk_mul_f32 v[64:65], v[64:65], v[96:97] op_sel_hi:[1,0]
	v_pk_mul_f32 v[66:67], v[66:67], v[96:97] op_sel_hi:[1,0]
	v_pk_fma_f32 v[64:65], v[0:1], v[64:65], v[8:9]
	v_pk_fma_f32 v[66:67], v[2:3], v[66:67], v[10:11]
	v_pk_mul_f32 v[68:69], v[68:69], v[96:97] op_sel_hi:[1,0]
	v_pk_mul_f32 v[70:71], v[70:71], v[96:97] op_sel_hi:[1,0]
	v_cvt_pk_f16_f32 v99, v66, v67
	v_cvt_pk_f16_f32 v98, v64, v65
	v_lshl_add_u64 v[100:101], v[130:131], 0, s[16:17]
	v_pk_fma_f32 v[70:71], v[6:7], v[70:71], v[14:15]
	v_pk_fma_f32 v[68:69], v[4:5], v[68:69], v[12:13]
	v_pk_mul_f32 v[74:75], v[74:75], v[96:97] op_sel_hi:[1,0]
	v_pk_mul_f32 v[72:73], v[72:73], v[96:97] op_sel_hi:[1,0]
	global_store_dwordx2 v[100:101], v[98:99], off
	v_cvt_pk_f16_f32 v99, v70, v71
	v_cvt_pk_f16_f32 v98, v68, v69
	v_pk_fma_f32 v[72:73], v[16:17], v[72:73], v[24:25]
	v_pk_fma_f32 v[74:75], v[18:19], v[74:75], v[26:27]
	v_pk_mul_f32 v[78:79], v[78:79], v[96:97] op_sel_hi:[1,0]
	v_pk_mul_f32 v[76:77], v[76:77], v[96:97] op_sel_hi:[1,0]
	global_store_dwordx2 v[100:101], v[98:99], off offset:512
	v_cvt_pk_f16_f32 v99, v74, v75
	v_cvt_pk_f16_f32 v98, v72, v73
	v_pk_fma_f32 v[76:77], v[20:21], v[76:77], v[28:29]
	v_pk_fma_f32 v[78:79], v[22:23], v[78:79], v[30:31]
	v_pk_mul_f32 v[80:81], v[80:81], v[96:97] op_sel_hi:[1,0]
	v_pk_mul_f32 v[82:83], v[82:83], v[96:97] op_sel_hi:[1,0]
	global_store_dwordx2 v[100:101], v[98:99], off offset:1024
	v_cvt_pk_f16_f32 v99, v78, v79
	v_cvt_pk_f16_f32 v98, v76, v77
	v_pk_fma_f32 v[82:83], v[34:35], v[82:83], v[42:43]
	v_pk_fma_f32 v[80:81], v[32:33], v[80:81], v[40:41]
	v_pk_mul_f32 v[86:87], v[86:87], v[96:97] op_sel_hi:[1,0]
	v_pk_mul_f32 v[84:85], v[84:85], v[96:97] op_sel_hi:[1,0]
	global_store_dwordx2 v[100:101], v[98:99], off offset:1536
	v_cvt_pk_f16_f32 v99, v82, v83
	v_cvt_pk_f16_f32 v98, v80, v81
	v_pk_fma_f32 v[84:85], v[36:37], v[84:85], v[44:45]
	v_pk_fma_f32 v[86:87], v[38:39], v[86:87], v[46:47]
	v_pk_mul_f32 v[90:91], v[90:91], v[96:97] op_sel_hi:[1,0]
	v_pk_mul_f32 v[88:89], v[88:89], v[96:97] op_sel_hi:[1,0]
	v_pk_mul_f32 v[92:93], v[92:93], v[96:97] op_sel_hi:[1,0]
	v_pk_mul_f32 v[94:95], v[94:95], v[96:97] op_sel_hi:[1,0]
	global_store_dwordx2 v[100:101], v[98:99], off offset:2048
	v_cvt_pk_f16_f32 v99, v86, v87
	v_cvt_pk_f16_f32 v98, v84, v85
	v_pk_fma_f32 v[88:89], v[48:49], v[88:89], v[56:57]
	v_pk_fma_f32 v[90:91], v[50:51], v[90:91], v[58:59]
	v_pk_fma_f32 v[94:95], v[54:55], v[94:95], v[62:63]
	v_pk_fma_f32 v[92:93], v[52:53], v[92:93], v[60:61]
	global_store_dwordx2 v[100:101], v[98:99], off offset:2560
	v_cvt_pk_f16_f32 v99, v90, v91
	v_cvt_pk_f16_f32 v98, v88, v89
	v_cvt_pk_f16_f32 v97, v94, v95
	v_cvt_pk_f16_f32 v96, v92, v93
	global_store_dwordx2 v[100:101], v[98:99], off offset:3072
	global_store_dwordx2 v[100:101], v[96:97], off offset:3584
	v_mov_b32_e32 v96, v68
	v_mov_b32_e32 v97, v64
	v_mov_b32_e32 v98, v69
	v_mov_b32_e32 v99, v65
	v_pk_add_f32 v[96:97], v[96:97], v[98:99]
	v_mov_b32_e32 v98, v70
	v_mov_b32_e32 v99, v66
	v_mov_b32_e32 v100, v71
	v_mov_b32_e32 v101, v67
	v_pk_add_f32 v[98:99], v[98:99], v[100:101]
	v_mov_b32_e32 v100, v72
	v_pk_add_f32 v[96:97], v[96:97], v[98:99]
	v_pk_mov_b32 v[98:99], v[72:73], v[74:75] op_sel:[1,0]
	v_mov_b32_e32 v101, v75
	v_pk_add_f32 v[98:99], v[98:99], v[100:101]
	v_add_f32_e32 v97, 0, v97
	v_pk_add_f32 v[98:99], v[98:99], v[98:99] op_sel_hi:[0,1]
	v_add_f32_e32 v97, v96, v97
	v_add_f32_e32 v101, v76, v77
	v_add_f32_e32 v103, v78, v79
	v_mov_b32_e32 v100, v80
	v_mov_b32_e32 v102, v81
	v_mov_b32_e32 v98, v82
	v_mov_b32_e32 v96, v83
	v_pk_add_f32 v[100:101], v[100:101], v[102:103]
	v_pk_add_f32 v[96:97], v[98:99], v[96:97]
	v_pk_mov_b32 v[98:99], v[84:85], v[86:87] op_sel:[1,0]
	v_pk_add_f32 v[96:97], v[100:101], v[96:97]
	v_mov_b32_e32 v100, v84
	v_mov_b32_e32 v101, v87
	v_pk_add_f32 v[98:99], v[98:99], v[100:101]
	v_pk_add_f32 v[96:97], v[96:97], v[96:97] op_sel_hi:[0,1]
	v_pk_add_f32 v[98:99], v[98:99], v[98:99] op_sel_hi:[0,1]
	v_add_f32_e32 v101, v88, v89
	v_add_f32_e32 v103, v90, v91
	v_mov_b32_e32 v100, v92
	v_mov_b32_e32 v102, v93
	v_mov_b32_e32 v98, v94
	v_mov_b32_e32 v96, v95
	v_pk_add_f32 v[100:101], v[100:101], v[102:103]
	v_pk_add_f32 v[96:97], v[98:99], v[96:97]
	v_mov_b32_e32 v136, v64
	v_pk_add_f32 v[96:97], v[100:101], v[96:97]
	v_mov_b32_e32 v126, v68
	v_add_f32_e32 v96, v96, v97
	ds_bpermute_b32 v97, v170, v96
	v_mov_b32_e32 v110, v66
	v_mov_b32_e32 v124, v70
	v_mov_b32_e32 v120, v72
	v_mov_b32_e32 v122, v74
	s_waitcnt lgkmcnt(0)
	v_add_f32_e32 v96, v96, v97
	ds_bpermute_b32 v97, v171, v96
	v_mov_b32_e32 v116, v76
	v_mov_b32_e32 v118, v78
	v_mov_b32_e32 v112, v82
	v_mov_b32_e32 v114, v80
	s_waitcnt lgkmcnt(0)
	v_add_f32_e32 v96, v96, v97
	ds_bpermute_b32 v97, v172, v96
	v_mov_b32_e32 v104, v84
	v_mov_b32_e32 v106, v86
	s_waitcnt lgkmcnt(0)
	v_add_f32_e32 v96, v96, v97
	ds_bpermute_b32 v97, v173, v96
	s_waitcnt lgkmcnt(0)
	v_add_f32_e32 v96, v96, v97
	ds_bpermute_b32 v97, v174, v96
	s_waitcnt lgkmcnt(0)
	v_add_f32_e32 v96, v96, v97
	ds_bpermute_b32 v97, v175, v96
	s_waitcnt lgkmcnt(0)
	v_add_f32_e32 v144, v96, v97
	v_fmamk_f32 v137, v144, 0xba000000, v65
	v_fmamk_f32 v127, v144, 0xba000000, v69
	v_fmamk_f32 v111, v144, 0xba000000, v67
	v_fmac_f32_e32 v136, 0xba000000, v144
	v_fmamk_f32 v125, v144, 0xba000000, v71
	v_fmac_f32_e32 v126, 0xba000000, v144
	v_mov_b32_e32 v98, v137
	v_mov_b32_e32 v99, v127
	v_fmac_f32_e32 v110, 0xba000000, v144
	v_fmac_f32_e32 v124, 0xba000000, v144
	v_mov_b32_e32 v96, v136
	v_mov_b32_e32 v97, v126
	v_pk_mul_f32 v[98:99], v[98:99], v[98:99]
	v_mov_b32_e32 v100, v111
	v_mov_b32_e32 v101, v125
	v_pk_fma_f32 v[96:97], v[96:97], v[96:97], v[98:99]
	v_mov_b32_e32 v98, v110
	v_mov_b32_e32 v99, v124
	v_pk_mul_f32 v[100:101], v[100:101], v[100:101]
	v_fmamk_f32 v121, v144, 0xba000000, v73
	v_pk_fma_f32 v[98:99], v[98:99], v[98:99], v[100:101]
	v_fmac_f32_e32 v120, 0xba000000, v144
	v_pk_add_f32 v[96:97], v[96:97], v[98:99]
	v_fmamk_f32 v123, v144, 0xba000000, v75
	v_fmac_f32_e32 v122, 0xba000000, v144
	v_pk_add_f32 v[96:97], v[96:97], v[96:97] op_sel_hi:[0,1]
	v_pk_mul_f32 v[98:99], v[122:123], v[122:123]
	v_pk_mul_f32 v[100:101], v[120:121], v[120:121]
	v_fmac_f32_e32 v116, 0xba000000, v144
	v_pk_mov_b32 v[102:103], v[100:101], v[98:99] op_sel:[1,0]
	v_mov_b32_e32 v101, v99
	v_fmamk_f32 v117, v144, 0xba000000, v77
	v_fmac_f32_e32 v118, 0xba000000, v144
	v_mul_f32_e32 v96, v116, v116
	v_pk_add_f32 v[98:99], v[102:103], v[100:101]
	v_fmamk_f32 v119, v144, 0xba000000, v79
	v_pk_fma_f32 v[100:101], v[116:117], v[116:117], v[96:97] op_sel_hi:[1,1,0]
	v_mul_f32_e32 v96, v118, v118
	v_pk_add_f32 v[98:99], v[98:99], v[98:99] op_sel_hi:[0,1]
	v_pk_fma_f32 v[102:103], v[118:119], v[118:119], v[96:97] op_sel_hi:[1,1,0]
	v_fmamk_f32 v113, v144, 0xba000000, v83
	v_fmac_f32_e32 v112, 0xba000000, v144
	v_fmamk_f32 v115, v144, 0xba000000, v81
	v_fmac_f32_e32 v114, 0xba000000, v144
	v_mul_f32_e32 v100, v114, v114
	v_mul_f32_e32 v102, v115, v115
	v_mul_f32_e32 v98, v112, v112
	v_mul_f32_e32 v96, v113, v113
	v_pk_add_f32 v[100:101], v[100:101], v[102:103]
	v_pk_add_f32 v[96:97], v[98:99], v[96:97]
	v_fmamk_f32 v105, v144, 0xba000000, v85
	v_pk_add_f32 v[96:97], v[100:101], v[96:97]
	v_fmac_f32_e32 v104, 0xba000000, v144
	v_fmamk_f32 v107, v144, 0xba000000, v87
	v_fmac_f32_e32 v106, 0xba000000, v144
	v_pk_add_f32 v[108:109], v[96:97], v[96:97] op_sel_hi:[0,1]
	v_pk_mul_f32 v[96:97], v[106:107], v[106:107]
	v_pk_mul_f32 v[98:99], v[104:105], v[104:105]
	v_mov_b32_e32 v102, v90
	v_pk_mov_b32 v[100:101], v[98:99], v[96:97] op_sel:[1,0]
	v_mov_b32_e32 v99, v97
	v_pk_add_f32 v[96:97], v[100:101], v[98:99]
	v_mov_b32_e32 v100, v88
	v_fmac_f32_e32 v100, 0xba000000, v144
	v_pk_add_f32 v[138:139], v[96:97], v[96:97] op_sel_hi:[0,1]
	v_fmamk_f32 v101, v144, 0xba000000, v89
	v_fmac_f32_e32 v102, 0xba000000, v144
	v_mul_f32_e32 v96, v100, v100
	v_fmamk_f32 v103, v144, 0xba000000, v91
	v_pk_fma_f32 v[140:141], v[100:101], v[100:101], v[96:97] op_sel_hi:[1,1,0]
	v_mul_f32_e32 v96, v102, v102
	v_pk_fma_f32 v[142:143], v[102:103], v[102:103], v[96:97] op_sel_hi:[1,1,0]
	v_mov_b32_e32 v96, v94
	v_mov_b32_e32 v98, v92
	v_fmamk_f32 v97, v144, 0xba000000, v95
	v_fmac_f32_e32 v96, 0xba000000, v144
	v_fmamk_f32 v99, v144, 0xba000000, v93
	v_fmac_f32_e32 v98, 0xba000000, v144
	v_mul_f32_e32 v140, v98, v98
	v_mul_f32_e32 v142, v99, v99
	v_mul_f32_e32 v138, v96, v96
	v_mul_f32_e32 v108, v97, v97
	v_pk_add_f32 v[140:141], v[140:141], v[142:143]
	v_pk_add_f32 v[108:109], v[138:139], v[108:109]
	s_nop 0
	v_pk_add_f32 v[108:109], v[140:141], v[108:109]
	s_nop 0
	v_add_f32_e32 v108, v108, v109
	ds_bpermute_b32 v109, v170, v108
	s_waitcnt lgkmcnt(0)
	v_add_f32_e32 v108, v108, v109
	ds_bpermute_b32 v109, v171, v108
	s_waitcnt lgkmcnt(0)
	v_add_f32_e32 v108, v108, v109
	ds_bpermute_b32 v109, v172, v108
	s_waitcnt lgkmcnt(0)
	v_add_f32_e32 v108, v108, v109
	ds_bpermute_b32 v109, v173, v108
	s_waitcnt lgkmcnt(0)
	v_add_f32_e32 v108, v108, v109
	ds_bpermute_b32 v109, v174, v108
	s_waitcnt lgkmcnt(0)
	v_add_f32_e32 v108, v108, v109
	ds_bpermute_b32 v109, v175, v108
	s_waitcnt lgkmcnt(0)
	v_add_f32_e32 v108, v108, v109
	v_fmamk_f32 v108, v108, 0x3a000000, v229
	v_cmp_gt_f32_e32 vcc, s5, v108
	v_mul_f32_e32 v109, 0x4f800000, v108
	s_nop 0
	v_cndmask_b32_e32 v108, v108, v109, vcc
	v_sqrt_f32_e32 v109, v108
	s_nop 0
	v_add_u32_e32 v138, -1, v109
	v_fma_f32 v139, -v138, v109, v108
	v_cmp_ge_f32_e64 s[6:7], 0, v139
	v_add_u32_e32 v139, 1, v109
	s_nop 0
	v_cndmask_b32_e64 v138, v109, v138, s[6:7]
	v_fma_f32 v109, -v139, v109, v108
	v_cmp_lt_f32_e64 s[6:7], 0, v109
	s_nop 1
	v_cndmask_b32_e64 v109, v138, v139, s[6:7]
	v_mul_f32_e32 v138, 0x37800000, v109
	v_cndmask_b32_e32 v109, v109, v138, vcc
	v_cmp_class_f32_e32 vcc, v108, v230
	s_nop 1
	v_cndmask_b32_e32 v108, v109, v108, vcc
	v_div_scale_f32 v109, s[6:7], v108, v108, 1.0
	v_rcp_f32_e32 v138, v109
	s_nop 0
	v_fma_f32 v139, -v109, v138, 1.0
	v_fmac_f32_e32 v138, v139, v138
	v_div_scale_f32 v139, vcc, 1.0, v108, 1.0
	v_mul_f32_e32 v140, v139, v138
	v_fma_f32 v141, -v109, v140, v139
	v_fmac_f32_e32 v140, v141, v138
	v_fma_f32 v109, -v109, v140, v139
	v_div_fmas_f32 v109, v109, v138, v140
	v_div_fixup_f32 v108, v109, v108, 1.0
	v_add_u32_e32 v109, s14, v176
	ds_read_b128 v[138:141], v109 offset:24576
	ds_read_b128 v[146:149], v109 offset:32768
	v_pk_mul_f32 v[136:137], v[136:137], v[108:109] op_sel_hi:[1,0]
	v_pk_mul_f32 v[110:111], v[110:111], v[108:109] op_sel_hi:[1,0]
	v_pk_mul_f32 v[126:127], v[126:127], v[108:109] op_sel_hi:[1,0]
	v_pk_mul_f32 v[124:125], v[124:125], v[108:109] op_sel_hi:[1,0]
	s_waitcnt lgkmcnt(0)
	v_pk_add_f32 v[146:147], v[146:147], 1.0 op_sel_hi:[1,0]
	v_pk_add_f32 v[142:143], v[148:149], 1.0 op_sel_hi:[1,0]
	v_pk_fma_f32 v[136:137], v[146:147], v[136:137], v[138:139]
	v_pk_fma_f32 v[110:111], v[142:143], v[110:111], v[140:141]
	v_cvt_pk_bf16_f32 v136, v136, v137
	v_cvt_pk_bf16_f32 v137, v110, v111
	v_lshl_add_u64 v[110:111], v[132:133], 0, s[16:17]
	global_store_dwordx2 v[110:111], v[136:137], off
	ds_read_b128 v[136:139], v109 offset:25600
	ds_read_b128 v[140:143], v109 offset:33792
	v_pk_mul_f32 v[120:121], v[120:121], v[108:109] op_sel_hi:[1,0]
	v_pk_mul_f32 v[122:123], v[122:123], v[108:109] op_sel_hi:[1,0]
	v_pk_mul_f32 v[116:117], v[116:117], v[108:109] op_sel_hi:[1,0]
	v_pk_mul_f32 v[118:119], v[118:119], v[108:109] op_sel_hi:[1,0]
	s_waitcnt lgkmcnt(0)
	v_pk_add_f32 v[140:141], v[140:141], 1.0 op_sel_hi:[1,0]
	v_pk_add_f32 v[142:143], v[142:143], 1.0 op_sel_hi:[1,0]
	v_pk_fma_f32 v[126:127], v[140:141], v[126:127], v[136:137]
	v_pk_fma_f32 v[124:125], v[142:143], v[124:125], v[138:139]
	v_cvt_pk_bf16_f32 v126, v126, v127
	v_cvt_pk_bf16_f32 v127, v124, v125
	global_store_dwordx2 v[110:111], v[126:127], off offset:512
	ds_read_b128 v[124:127], v109 offset:26624
	ds_read_b128 v[136:139], v109 offset:34816
	v_pk_mul_f32 v[114:115], v[114:115], v[108:109] op_sel_hi:[1,0]
	v_pk_mul_f32 v[112:113], v[112:113], v[108:109] op_sel_hi:[1,0]
	v_pk_mul_f32 v[104:105], v[104:105], v[108:109] op_sel_hi:[1,0]
	v_pk_mul_f32 v[106:107], v[106:107], v[108:109] op_sel_hi:[1,0]
	s_waitcnt lgkmcnt(0)
	v_pk_add_f32 v[136:137], v[136:137], 1.0 op_sel_hi:[1,0]
	v_pk_add_f32 v[138:139], v[138:139], 1.0 op_sel_hi:[1,0]
	v_pk_fma_f32 v[120:121], v[136:137], v[120:121], v[124:125]
	v_pk_fma_f32 v[122:123], v[138:139], v[122:123], v[126:127]
	v_cvt_pk_bf16_f32 v120, v120, v121
	v_cvt_pk_bf16_f32 v121, v122, v123
	global_store_dwordx2 v[110:111], v[120:121], off offset:1024
	ds_read_b128 v[120:123], v109 offset:27648
	ds_read_b128 v[124:127], v109 offset:35840
	v_pk_mul_f32 v[100:101], v[100:101], v[108:109] op_sel_hi:[1,0]
	v_pk_mul_f32 v[102:103], v[102:103], v[108:109] op_sel_hi:[1,0]
	v_pk_mul_f32 v[98:99], v[98:99], v[108:109] op_sel_hi:[1,0]
	v_pk_mul_f32 v[96:97], v[96:97], v[108:109] op_sel_hi:[1,0]
	s_waitcnt lgkmcnt(0)
	v_pk_add_f32 v[124:125], v[124:125], 1.0 op_sel_hi:[1,0]
	v_pk_add_f32 v[126:127], v[126:127], 1.0 op_sel_hi:[1,0]
	v_pk_fma_f32 v[116:117], v[124:125], v[116:117], v[120:121]
	v_pk_fma_f32 v[118:119], v[126:127], v[118:119], v[122:123]
	v_cvt_pk_bf16_f32 v116, v116, v117
	v_cvt_pk_bf16_f32 v117, v118, v119
	global_store_dwordx2 v[110:111], v[116:117], off offset:1536
	ds_read_b128 v[116:119], v109 offset:28672
	ds_read_b128 v[120:123], v109 offset:36864
	s_waitcnt lgkmcnt(0)
	v_pk_add_f32 v[120:121], v[120:121], 1.0 op_sel_hi:[1,0]
	s_nop 0
	v_pk_fma_f32 v[114:115], v[120:121], v[114:115], v[116:117]
	v_pk_add_f32 v[122:123], v[122:123], 1.0 op_sel_hi:[1,0]
	v_pk_fma_f32 v[112:113], v[122:123], v[112:113], v[118:119]
	v_cvt_pk_bf16_f32 v114, v114, v115
	v_cvt_pk_bf16_f32 v115, v112, v113
	global_store_dwordx2 v[110:111], v[114:115], off offset:2048
	ds_read_b128 v[112:115], v109 offset:29696
	ds_read_b128 v[116:119], v109 offset:37888
	s_waitcnt lgkmcnt(0)
	v_pk_add_f32 v[116:117], v[116:117], 1.0 op_sel_hi:[1,0]
	s_nop 0
	v_pk_fma_f32 v[104:105], v[116:117], v[104:105], v[112:113]
	v_pk_add_f32 v[118:119], v[118:119], 1.0 op_sel_hi:[1,0]
	v_pk_fma_f32 v[106:107], v[118:119], v[106:107], v[114:115]
	v_cvt_pk_bf16_f32 v104, v104, v105
	v_cvt_pk_bf16_f32 v105, v106, v107
	global_store_dwordx2 v[110:111], v[104:105], off offset:2560
	ds_read_b128 v[104:107], v109 offset:30720
	ds_read_b128 v[112:115], v109 offset:38912
	s_waitcnt lgkmcnt(0)
	v_pk_add_f32 v[112:113], v[112:113], 1.0 op_sel_hi:[1,0]
	s_nop 0
	v_pk_fma_f32 v[100:101], v[112:113], v[100:101], v[104:105]
	v_pk_add_f32 v[114:115], v[114:115], 1.0 op_sel_hi:[1,0]
	v_pk_fma_f32 v[102:103], v[114:115], v[102:103], v[106:107]
	v_cvt_pk_bf16_f32 v100, v100, v101
	v_cvt_pk_bf16_f32 v101, v102, v103
	global_store_dwordx2 v[110:111], v[100:101], off offset:3072
	ds_read_b128 v[100:103], v109 offset:31744
	ds_read_b128 v[104:107], v109 offset:39936
	s_waitcnt lgkmcnt(0)
	v_pk_add_f32 v[104:105], v[104:105], 1.0 op_sel_hi:[1,0]
	s_nop 0
	v_pk_fma_f32 v[98:99], v[104:105], v[98:99], v[100:101]
	v_pk_add_f32 v[106:107], v[106:107], 1.0 op_sel_hi:[1,0]
	v_pk_fma_f32 v[96:97], v[106:107], v[96:97], v[102:103]
	v_cvt_pk_bf16_f32 v98, v98, v99
	v_cvt_pk_bf16_f32 v99, v96, v97
	global_store_dwordx2 v[110:111], v[98:99], off offset:3584
	s_branch .LBB0_918
.LBB0_923:
	v_readlane_b32 s6, v253, 54
	v_readlane_b32 s4, v255, 15
	v_readlane_b32 s7, v253, 55
	v_readlane_b32 s5, v255, 16
	s_and_b64 vcc, exec, s[4:5]
	v_cndmask_b32_e64 v0, 0, 1, s[6:7]
	v_cmp_ne_u32_e64 s[4:5], 1, v0
	s_barrier
	s_nop 0
	s_nop 1
	v_writelane_b32 v255, s4, 39
	s_nop 1
	v_writelane_b32 v255, s5, 40
	s_nop 0
	v_readlane_b32 s48, v255, 0
	s_cbranch_vccnz .LBB0_928
	v_mbcnt_lo_u32_b32 v0, -1, 0
	v_mbcnt_hi_u32_b32 v0, -1, v0
	s_mov_b32 s4, 0xffff0000
	v_add_u32_e32 v0, s66, v0
	s_load_dwordx2 s[14:15], s[0:1], 0xd0
	s_load_dwordx4 s[16:19], s[0:1], 0x80
	v_lshlrev_b32_e32 v2, 2, v0
	v_ashrrev_i32_e32 v3, 31, v2
	v_lshlrev_b64 v[10:11], 2, v[2:3]
	v_lshl_add_u32 v1, v0, 4, 0
	s_waitcnt lgkmcnt(0)
	s_add_u32 s0, s16, s64
	s_addc_u32 s1, s17, s65
	s_add_u32 s16, s18, s64
	s_addc_u32 s17, s19, s65
	v_lshl_add_u64 v[2:3], s[0:1], 0, v[10:11]
	global_load_dwordx4 v[2:5], v[2:3], off
	v_lshl_add_u64 v[6:7], s[16:17], 0, v[10:11]
	global_load_dwordx4 v[6:9], v[6:7], off
	s_add_u32 s0, s14, s50
	s_addc_u32 s1, s15, s51
	v_lshl_add_u64 v[10:11], s[0:1], 0, v[10:11]
	s_mov_b32 s0, 0x134000
	s_mov_b32 s5, 0xf800000
	s_mov_b32 s8, 0x3fb504f3
	s_waitcnt vmcnt(1)
	ds_write_b128 v1, v[2:5]
	s_waitcnt vmcnt(0)
	ds_write_b128 v1, v[6:9] offset:8192
	v_add_co_u32_e32 v2, vcc, s0, v10
	v_readlane_b32 s0, v255, 39
	s_nop 0
	v_addc_co_u32_e32 v3, vcc, 0, v11, vcc
	v_add_co_u32_e32 v6, vcc, 0x136000, v10
	global_load_dwordx4 v[2:5], v[2:3], off
	s_nop 0
	v_addc_co_u32_e32 v7, vcc, 0, v11, vcc
	v_add_co_u32_e32 v10, vcc, 0x138000, v10
	global_load_dwordx4 v[6:9], v[6:7], off
	s_nop 0
	v_addc_co_u32_e32 v11, vcc, 0, v11, vcc
	global_load_dwordx4 v[10:13], v[10:11], off
	v_readlane_b32 s1, v255, 40
	s_and_b64 vcc, exec, s[0:1]
	s_waitcnt vmcnt(2)
	ds_write_b128 v1, v[2:5] offset:16384
	s_waitcnt vmcnt(1)
	ds_write_b128 v1, v[6:9] offset:24576
	s_waitcnt vmcnt(0)
	ds_write_b128 v1, v[10:13] offset:32768
	s_waitcnt lgkmcnt(0)
	s_barrier
	s_cbranch_vccnz .LBB0_927
	v_readlane_b32 s0, v254, 25
	v_readlane_b32 s1, v254, 26
	s_add_u32 s0, s14, s0
	s_addc_u32 s1, s15, s1
	v_readlane_b32 s6, v254, 41
	v_and_b32_e32 v0, 63, v0
	v_readlane_b32 s7, v254, 42
	s_add_u32 s16, s14, s6
	v_lshlrev_b32_e32 v1, 2, v0
	v_lshlrev_b32_e32 v2, 4, v0
	s_addc_u32 s17, s15, s7
	v_readlane_b32 s6, v254, 39
	v_xor_b32_e32 v82, 4, v1
	v_xor_b32_e32 v83, 8, v1
	v_xor_b32_e32 v84, 16, v1
	v_xor_b32_e32 v85, 32, v1
	v_xor_b32_e32 v86, 64, v1
	v_xor_b32_e32 v87, 0x80, v1
	v_lshlrev_b32_e32 v144, 3, v0
	v_add_u32_e32 v88, 0, v2
	s_mov_b32 s18, s6
	s_mov_b32 s6, 0x15000000
	v_readlane_b32 s7, v254, 40

.LBB0_1260:
	v_readlane_b32 s4, v254, 45
	v_readlane_b32 s5, v254, 46
	s_and_b64 vcc, exec, s[4:5]
	s_cbranch_vccz .LBB0_1262
	v_mov_b32_e32 v140, v116
	v_mov_b32_e32 v141, v124
	v_mov_b32_e32 v142, v117
	v_mov_b32_e32 v143, v125
	v_pk_add_f32 v[140:141], v[140:141], v[142:143]
	v_mov_b32_e32 v142, v118
	v_mov_b32_e32 v143, v126
	v_mov_b32_e32 v146, v119
	v_mov_b32_e32 v147, v127
	v_pk_add_f32 v[142:143], v[142:143], v[146:147]
	v_mov_b32_e32 v146, v120
	v_pk_add_f32 v[140:141], v[140:141], v[142:143]
	v_mov_b32_e32 v142, v121
	v_mov_b32_e32 v143, v122
	v_mov_b32_e32 v147, v123
	v_pk_add_f32 v[142:143], v[142:143], v[146:147]
	v_add_f32_e32 v141, 0, v141
	v_pk_add_f32 v[142:143], v[142:143], v[142:143] op_sel_hi:[0,1]
	v_add_f32_e32 v141, v140, v141
	v_add_f32_e32 v147, v108, v109
	v_add_f32_e32 v149, v110, v111
	v_mov_b32_e32 v146, v112
	v_mov_b32_e32 v148, v113
	v_mov_b32_e32 v142, v114
	v_mov_b32_e32 v140, v115
	v_pk_add_f32 v[146:147], v[146:147], v[148:149]
	v_pk_add_f32 v[140:141], v[142:143], v[140:141]
	v_mov_b32_e32 v142, v101
	v_pk_add_f32 v[140:141], v[146:147], v[140:141]
	v_mov_b32_e32 v143, v102
	v_mov_b32_e32 v146, v100
	v_mov_b32_e32 v147, v103
	v_pk_add_f32 v[142:143], v[142:143], v[146:147]
	v_pk_add_f32 v[140:141], v[140:141], v[140:141] op_sel_hi:[0,1]
	v_pk_add_f32 v[142:143], v[142:143], v[142:143] op_sel_hi:[0,1]
	v_add_f32_e32 v147, v104, v105
	v_add_f32_e32 v149, v106, v107
	v_mov_b32_e32 v146, v96
	v_mov_b32_e32 v148, v97
	v_mov_b32_e32 v142, v98
	v_mov_b32_e32 v140, v99
	v_pk_add_f32 v[146:147], v[146:147], v[148:149]
	v_pk_add_f32 v[140:141], v[142:143], v[140:141]
	s_mov_b32 s4, 0xf800000
	v_pk_add_f32 v[140:141], v[146:147], v[140:141]
	s_nop 0
	v_add_f32_e32 v140, v140, v141
	ds_bpermute_b32 v141, v129, v140
	s_waitcnt lgkmcnt(0)
	v_add_f32_e32 v140, v140, v141
	ds_bpermute_b32 v141, v182, v140
	s_waitcnt lgkmcnt(0)
	v_add_f32_e32 v140, v140, v141
	ds_bpermute_b32 v141, v183, v140
	s_waitcnt lgkmcnt(0)
	v_add_f32_e32 v140, v140, v141
	ds_bpermute_b32 v141, v184, v140
	s_waitcnt lgkmcnt(0)
	v_add_f32_e32 v140, v140, v141
	ds_bpermute_b32 v141, v185, v140
	s_waitcnt lgkmcnt(0)
	v_add_f32_e32 v140, v140, v141
	ds_bpermute_b32 v141, v186, v140
	s_waitcnt lgkmcnt(0)
	v_add_f32_e32 v150, v140, v141
	v_fmamk_f32 v125, v150, 0xba000000, v125
	v_fmamk_f32 v117, v150, 0xba000000, v117
	v_fmamk_f32 v127, v150, 0xba000000, v127
	v_fmac_f32_e32 v124, 0xba000000, v150
	v_fmamk_f32 v119, v150, 0xba000000, v119
	v_fmac_f32_e32 v116, 0xba000000, v150
	v_mov_b32_e32 v142, v125
	v_mov_b32_e32 v143, v117
	v_fmac_f32_e32 v126, 0xba000000, v150
	v_fmac_f32_e32 v118, 0xba000000, v150
	v_mov_b32_e32 v140, v124
	v_mov_b32_e32 v141, v116
	v_pk_mul_f32 v[142:143], v[142:143], v[142:143]
	v_mov_b32_e32 v146, v127
	v_mov_b32_e32 v147, v119
	v_pk_fma_f32 v[140:141], v[140:141], v[140:141], v[142:143]
	v_mov_b32_e32 v142, v126
	v_mov_b32_e32 v143, v118
	v_pk_mul_f32 v[146:147], v[146:147], v[146:147]
	v_fmamk_f32 v121, v150, 0xba000000, v121
	v_pk_fma_f32 v[142:143], v[142:143], v[142:143], v[146:147]
	v_fmac_f32_e32 v120, 0xba000000, v150
	v_pk_add_f32 v[140:141], v[140:141], v[142:143]
	v_fmamk_f32 v123, v150, 0xba000000, v123
	v_fmac_f32_e32 v122, 0xba000000, v150
	v_pk_add_f32 v[140:141], v[140:141], v[140:141] op_sel_hi:[0,1]
	v_pk_mul_f32 v[142:143], v[122:123], v[122:123]
	v_pk_mul_f32 v[146:147], v[120:121], v[120:121]
	v_fmac_f32_e32 v108, 0xba000000, v150
	v_pk_mov_b32 v[148:149], v[146:147], v[142:143] op_sel:[1,0]
	v_mov_b32_e32 v147, v143
	v_fmamk_f32 v109, v150, 0xba000000, v109
	v_fmac_f32_e32 v110, 0xba000000, v150
	v_mul_f32_e32 v140, v108, v108
	v_pk_add_f32 v[142:143], v[148:149], v[146:147]
	v_fmamk_f32 v111, v150, 0xba000000, v111
	v_pk_fma_f32 v[146:147], v[108:109], v[108:109], v[140:141] op_sel_hi:[1,1,0]
	v_mul_f32_e32 v140, v110, v110
	v_pk_add_f32 v[142:143], v[142:143], v[142:143] op_sel_hi:[0,1]
	v_pk_fma_f32 v[148:149], v[110:111], v[110:111], v[140:141] op_sel_hi:[1,1,0]
	v_fmamk_f32 v115, v150, 0xba000000, v115
	v_fmac_f32_e32 v114, 0xba000000, v150
	v_fmamk_f32 v113, v150, 0xba000000, v113
	v_fmac_f32_e32 v112, 0xba000000, v150
	v_mul_f32_e32 v146, v112, v112
	v_mul_f32_e32 v148, v113, v113
	v_mul_f32_e32 v142, v114, v114
	v_mul_f32_e32 v140, v115, v115
	v_pk_add_f32 v[146:147], v[146:147], v[148:149]
	v_pk_add_f32 v[140:141], v[142:143], v[140:141]
	v_fmamk_f32 v101, v150, 0xba000000, v101
	v_pk_add_f32 v[140:141], v[146:147], v[140:141]
	v_fmac_f32_e32 v100, 0xba000000, v150
	v_fmamk_f32 v103, v150, 0xba000000, v103
	v_fmac_f32_e32 v102, 0xba000000, v150
	v_pk_add_f32 v[140:141], v[140:141], v[140:141] op_sel_hi:[0,1]
	v_pk_mul_f32 v[142:143], v[102:103], v[102:103]
	v_pk_mul_f32 v[146:147], v[100:101], v[100:101]
	v_fmac_f32_e32 v104, 0xba000000, v150
	v_pk_mov_b32 v[148:149], v[146:147], v[142:143] op_sel:[1,0]
	v_mov_b32_e32 v147, v143
	v_fmamk_f32 v105, v150, 0xba000000, v105
	v_fmac_f32_e32 v106, 0xba000000, v150
	v_mul_f32_e32 v140, v104, v104
	v_pk_add_f32 v[142:143], v[148:149], v[146:147]
	v_fmamk_f32 v107, v150, 0xba000000, v107
	v_pk_fma_f32 v[146:147], v[104:105], v[104:105], v[140:141] op_sel_hi:[1,1,0]
	v_mul_f32_e32 v140, v106, v106
	v_pk_add_f32 v[142:143], v[142:143], v[142:143] op_sel_hi:[0,1]
	v_pk_fma_f32 v[148:149], v[106:107], v[106:107], v[140:141] op_sel_hi:[1,1,0]
	v_fmamk_f32 v99, v150, 0xba000000, v99
	v_fmac_f32_e32 v98, 0xba000000, v150
	v_fmamk_f32 v97, v150, 0xba000000, v97
	v_fmac_f32_e32 v96, 0xba000000, v150
	v_mul_f32_e32 v146, v96, v96
	v_mul_f32_e32 v148, v97, v97
	v_mul_f32_e32 v142, v98, v98
	v_mul_f32_e32 v140, v99, v99
	v_pk_add_f32 v[146:147], v[146:147], v[148:149]
	v_pk_add_f32 v[140:141], v[142:143], v[140:141]
	s_nop 0
	v_pk_add_f32 v[140:141], v[146:147], v[140:141]
	s_nop 0
	v_add_f32_e32 v140, v140, v141
	ds_bpermute_b32 v141, v129, v140
	s_waitcnt lgkmcnt(0)
	v_add_f32_e32 v140, v140, v141
	ds_bpermute_b32 v141, v182, v140
	s_waitcnt lgkmcnt(0)
	v_add_f32_e32 v140, v140, v141
	ds_bpermute_b32 v141, v183, v140
	s_waitcnt lgkmcnt(0)
	v_add_f32_e32 v140, v140, v141
	ds_bpermute_b32 v141, v184, v140
	s_waitcnt lgkmcnt(0)
	v_add_f32_e32 v140, v140, v141
	ds_bpermute_b32 v141, v185, v140
	s_waitcnt lgkmcnt(0)
	v_add_f32_e32 v140, v140, v141
	ds_bpermute_b32 v141, v186, v140
	s_waitcnt lgkmcnt(0)
	v_add_f32_e32 v140, v140, v141
	v_fmamk_f32 v140, v140, 0x3a000000, v229
	v_cmp_gt_f32_e32 vcc, s4, v140
	v_mul_f32_e32 v141, 0x4f800000, v140
	s_mov_b32 s4, 0xffff0000
	v_cndmask_b32_e32 v140, v140, v141, vcc
	v_sqrt_f32_e32 v141, v140
	s_nop 0
	v_add_u32_e32 v142, -1, v141
	v_fma_f32 v143, -v142, v141, v140
	v_cmp_ge_f32_e64 s[8:9], 0, v143
	v_add_u32_e32 v143, 1, v141
	s_nop 0
	v_cndmask_b32_e64 v142, v141, v142, s[8:9]
	v_fma_f32 v141, -v143, v141, v140
	v_cmp_lt_f32_e64 s[8:9], 0, v141
	s_nop 1
	v_cndmask_b32_e64 v141, v142, v143, s[8:9]
	v_mul_f32_e32 v142, 0x37800000, v141
	v_cndmask_b32_e32 v141, v141, v142, vcc
	v_cmp_class_f32_e32 vcc, v140, v230
	s_nop 1
	v_cndmask_b32_e32 v140, v141, v140, vcc
	v_div_scale_f32 v141, s[8:9], v140, v140, 1.0
	v_rcp_f32_e32 v142, v141
	s_nop 0
	v_fma_f32 v143, -v141, v142, 1.0
	v_fmac_f32_e32 v142, v143, v142
	v_div_scale_f32 v143, vcc, 1.0, v140, 1.0
	v_mul_f32_e32 v146, v143, v142
	v_fma_f32 v147, -v141, v146, v143
	v_fmac_f32_e32 v146, v147, v142
	v_fma_f32 v141, -v141, v146, v143
	v_div_fmas_f32 v141, v141, v142, v146
	ds_read_b128 v[146:149], v191 offset:24576
	ds_read_b128 v[150:153], v191 offset:32768
	v_div_fixup_f32 v140, v141, v140, 1.0
	v_pk_mul_f32 v[124:125], v[124:125], v[140:141] op_sel_hi:[1,0]
	v_pk_mul_f32 v[126:127], v[126:127], v[140:141] op_sel_hi:[1,0]
	s_waitcnt lgkmcnt(0)
	v_pk_add_f32 v[150:151], v[150:151], 1.0 op_sel_hi:[1,0]
	s_nop 0
	v_pk_fma_f32 v[124:125], v[150:151], v[124:125], v[146:147]
	v_pk_add_f32 v[142:143], v[152:153], 1.0 op_sel_hi:[1,0]
	v_bfe_u32 v141, v124, 16, 1
	v_add3_u32 v124, v124, v141, s69
	v_bfe_u32 v141, v125, 16, 1
	v_pk_fma_f32 v[126:127], v[142:143], v[126:127], v[148:149]
	v_lshrrev_b32_e32 v124, 16, v124
	v_add3_u32 v125, v125, v141, s69
	v_and_or_b32 v124, v125, s4, v124
	v_cvt_pk_bf16_f32 v125, v126, v127
	global_store_dwordx2 v[136:137], v[124:125], off
	ds_read_b128 v[124:127], v191 offset:25600
	ds_read_b128 v[146:149], v191 offset:33792
	v_pk_mul_f32 v[116:117], v[116:117], v[140:141] op_sel_hi:[1,0]
	v_pk_mul_f32 v[118:119], v[118:119], v[140:141] op_sel_hi:[1,0]
	v_pk_mul_f32 v[120:121], v[120:121], v[140:141] op_sel_hi:[1,0]
	v_pk_mul_f32 v[122:123], v[122:123], v[140:141] op_sel_hi:[1,0]
	s_waitcnt lgkmcnt(0)
	v_pk_add_f32 v[146:147], v[146:147], 1.0 op_sel_hi:[1,0]
	v_pk_add_f32 v[142:143], v[148:149], 1.0 op_sel_hi:[1,0]
	v_pk_fma_f32 v[116:117], v[146:147], v[116:117], v[124:125]
	v_pk_fma_f32 v[118:119], v[142:143], v[118:119], v[126:127]
	v_cvt_pk_bf16_f32 v116, v116, v117
	v_cvt_pk_bf16_f32 v117, v118, v119
	global_store_dwordx2 v[136:137], v[116:117], off offset:512
	ds_read_b128 v[116:119], v191 offset:26624
	ds_read_b128 v[124:127], v191 offset:34816
	v_pk_mul_f32 v[108:109], v[108:109], v[140:141] op_sel_hi:[1,0]
	v_pk_mul_f32 v[110:111], v[110:111], v[140:141] op_sel_hi:[1,0]
	v_pk_mul_f32 v[112:113], v[112:113], v[140:141] op_sel_hi:[1,0]
	v_pk_mul_f32 v[114:115], v[114:115], v[140:141] op_sel_hi:[1,0]
	s_waitcnt lgkmcnt(0)
	v_pk_add_f32 v[124:125], v[124:125], 1.0 op_sel_hi:[1,0]
	v_pk_add_f32 v[126:127], v[126:127], 1.0 op_sel_hi:[1,0]
	v_pk_fma_f32 v[116:117], v[124:125], v[120:121], v[116:117]
	v_pk_fma_f32 v[118:119], v[126:127], v[122:123], v[118:119]
	v_cvt_pk_bf16_f32 v116, v116, v117
	v_cvt_pk_bf16_f32 v117, v118, v119
	global_store_dwordx2 v[136:137], v[116:117], off offset:1024
	ds_read_b128 v[116:119], v191 offset:27648
	ds_read_b128 v[120:123], v191 offset:35840
	v_pk_mul_f32 v[100:101], v[100:101], v[140:141] op_sel_hi:[1,0]
	v_pk_mul_f32 v[102:103], v[102:103], v[140:141] op_sel_hi:[1,0]
	v_pk_mul_f32 v[104:105], v[104:105], v[140:141] op_sel_hi:[1,0]
	v_pk_mul_f32 v[106:107], v[106:107], v[140:141] op_sel_hi:[1,0]
	s_waitcnt lgkmcnt(0)
	v_pk_add_f32 v[120:121], v[120:121], 1.0 op_sel_hi:[1,0]
	v_pk_add_f32 v[122:123], v[122:123], 1.0 op_sel_hi:[1,0]
	v_pk_fma_f32 v[108:109], v[120:121], v[108:109], v[116:117]
	v_pk_fma_f32 v[110:111], v[122:123], v[110:111], v[118:119]
	v_cvt_pk_bf16_f32 v108, v108, v109
	v_cvt_pk_bf16_f32 v109, v110, v111
	global_store_dwordx2 v[136:137], v[108:109], off offset:1536
	ds_read_b128 v[108:111], v191 offset:28672
	ds_read_b128 v[116:119], v191 offset:36864
	v_pk_mul_f32 v[96:97], v[96:97], v[140:141] op_sel_hi:[1,0]
	v_pk_mul_f32 v[98:99], v[98:99], v[140:141] op_sel_hi:[1,0]
	s_waitcnt lgkmcnt(0)
	v_pk_add_f32 v[116:117], v[116:117], 1.0 op_sel_hi:[1,0]
	s_nop 0
	v_pk_fma_f32 v[108:109], v[116:117], v[112:113], v[108:109]
	v_pk_add_f32 v[118:119], v[118:119], 1.0 op_sel_hi:[1,0]
	v_pk_fma_f32 v[110:111], v[118:119], v[114:115], v[110:111]
	v_cvt_pk_bf16_f32 v108, v108, v109
	v_cvt_pk_bf16_f32 v109, v110, v111
	global_store_dwordx2 v[136:137], v[108:109], off offset:2048
	ds_read_b128 v[108:111], v191 offset:29696
	ds_read_b128 v[112:115], v191 offset:37888
	s_waitcnt lgkmcnt(0)
	v_pk_add_f32 v[112:113], v[112:113], 1.0 op_sel_hi:[1,0]
	s_nop 0
	v_pk_fma_f32 v[100:101], v[112:113], v[100:101], v[108:109]
	v_pk_add_f32 v[114:115], v[114:115], 1.0 op_sel_hi:[1,0]
	v_pk_fma_f32 v[102:103], v[114:115], v[102:103], v[110:111]
	v_cvt_pk_bf16_f32 v100, v100, v101
	v_cvt_pk_bf16_f32 v101, v102, v103
	global_store_dwordx2 v[136:137], v[100:101], off offset:2560
	ds_read_b128 v[100:103], v191 offset:30720
	ds_read_b128 v[108:111], v191 offset:38912
	s_waitcnt lgkmcnt(0)
	v_pk_add_f32 v[108:109], v[108:109], 1.0 op_sel_hi:[1,0]
	s_nop 0
	v_pk_fma_f32 v[100:101], v[108:109], v[104:105], v[100:101]
	v_pk_add_f32 v[110:111], v[110:111], 1.0 op_sel_hi:[1,0]
	v_pk_fma_f32 v[102:103], v[110:111], v[106:107], v[102:103]
	v_cvt_pk_bf16_f32 v100, v100, v101
	v_cvt_pk_bf16_f32 v101, v102, v103
	global_store_dwordx2 v[136:137], v[100:101], off offset:3072
	ds_read_b128 v[100:103], v191 offset:31744
	ds_read_b128 v[104:107], v191 offset:39936
	s_waitcnt lgkmcnt(0)
	v_pk_add_f32 v[104:105], v[104:105], 1.0 op_sel_hi:[1,0]
	s_nop 0
	v_pk_fma_f32 v[96:97], v[104:105], v[96:97], v[100:101]
	v_pk_add_f32 v[106:107], v[106:107], 1.0 op_sel_hi:[1,0]
	v_pk_fma_f32 v[98:99], v[106:107], v[98:99], v[102:103]
	v_cvt_pk_bf16_f32 v96, v96, v97
	v_cvt_pk_bf16_f32 v97, v98, v99
	global_store_dwordx2 v[136:137], v[96:97], off offset:3584

.LBB0_1295:
	v_readlane_b32 s4, v255, 15
	v_readlane_b32 s5, v255, 16
	s_and_b64 vcc, exec, s[4:5]
	s_cbranch_vccnz .LBB0_1225
	v_mov_b32_e32 v96, v64
	v_mov_b32_e32 v97, v68
	v_mov_b32_e32 v98, v65
	v_mov_b32_e32 v99, v69
	v_pk_add_f32 v[96:97], v[96:97], v[98:99]
	v_mov_b32_e32 v98, v66
	v_mov_b32_e32 v99, v70
	v_mov_b32_e32 v100, v67
	v_mov_b32_e32 v101, v71
	v_pk_add_f32 v[98:99], v[98:99], v[100:101]
	v_mov_b32_e32 v100, v72
	v_pk_add_f32 v[96:97], v[96:97], v[98:99]
	v_mov_b32_e32 v98, v73
	v_mov_b32_e32 v99, v74
	v_mov_b32_e32 v101, v75
	v_pk_add_f32 v[98:99], v[98:99], v[100:101]
	v_add_f32_e32 v97, 0, v97
	v_pk_add_f32 v[98:99], v[98:99], v[98:99] op_sel_hi:[0,1]
	v_add_f32_e32 v97, v96, v97
	v_add_f32_e32 v101, v76, v77
	v_add_f32_e32 v103, v78, v79
	v_mov_b32_e32 v100, v80
	v_mov_b32_e32 v102, v81
	v_mov_b32_e32 v98, v82
	v_mov_b32_e32 v96, v83
	v_pk_add_f32 v[100:101], v[100:101], v[102:103]
	v_pk_add_f32 v[96:97], v[98:99], v[96:97]
	v_mov_b32_e32 v98, v85
	v_pk_add_f32 v[96:97], v[100:101], v[96:97]
	v_mov_b32_e32 v99, v86
	v_mov_b32_e32 v100, v84
	v_mov_b32_e32 v101, v87
	v_pk_add_f32 v[98:99], v[98:99], v[100:101]
	v_pk_add_f32 v[96:97], v[96:97], v[96:97] op_sel_hi:[0,1]
	v_pk_add_f32 v[98:99], v[98:99], v[98:99] op_sel_hi:[0,1]
	v_add_f32_e32 v101, v88, v89
	v_add_f32_e32 v103, v90, v91
	v_mov_b32_e32 v100, v92
	v_mov_b32_e32 v102, v93
	v_mov_b32_e32 v98, v94
	v_mov_b32_e32 v96, v95
	v_pk_add_f32 v[100:101], v[100:101], v[102:103]
	v_pk_add_f32 v[96:97], v[98:99], v[96:97]
	v_mov_b32_e32 v140, v68
	v_pk_add_f32 v[96:97], v[100:101], v[96:97]
	v_mov_b32_e32 v152, v64
	v_add_f32_e32 v96, v96, v97
	ds_bpermute_b32 v97, v129, v96
	v_mov_b32_e32 v126, v70
	v_mov_b32_e32 v150, v66
	v_mov_b32_e32 v154, v72
	v_mov_b32_e32 v156, v74
	s_waitcnt lgkmcnt(0)
	v_add_f32_e32 v96, v96, v97
	ds_bpermute_b32 v97, v182, v96
	v_mov_b32_e32 v114, v76
	v_mov_b32_e32 v116, v78
	v_mov_b32_e32 v108, v82
	v_mov_b32_e32 v112, v80
	s_waitcnt lgkmcnt(0)
	v_add_f32_e32 v96, v96, v97
	ds_bpermute_b32 v97, v183, v96
	v_mov_b32_e32 v104, v84
	v_mov_b32_e32 v106, v86
	s_mov_b32 s4, 0xf800000
	s_lshr_b32 s6, s16, 12
	s_waitcnt lgkmcnt(0)
	v_add_f32_e32 v96, v96, v97
	ds_bpermute_b32 v97, v184, v96
	s_mulk_i32 s6, 0x6000
	s_waitcnt lgkmcnt(0)
	v_add_f32_e32 v96, v96, v97
	ds_bpermute_b32 v97, v185, v96
	s_waitcnt lgkmcnt(0)
	v_add_f32_e32 v96, v96, v97
	ds_bpermute_b32 v97, v186, v96
	s_waitcnt lgkmcnt(0)
	v_add_f32_e32 v124, v96, v97
	v_fmamk_f32 v141, v124, 0xba000000, v69
	v_fmamk_f32 v153, v124, 0xba000000, v65
	v_fmamk_f32 v127, v124, 0xba000000, v71
	v_fmac_f32_e32 v140, 0xba000000, v124
	v_fmamk_f32 v151, v124, 0xba000000, v67
	v_fmac_f32_e32 v152, 0xba000000, v124
	v_mov_b32_e32 v98, v141
	v_mov_b32_e32 v99, v153
	v_fmac_f32_e32 v126, 0xba000000, v124
	v_fmac_f32_e32 v150, 0xba000000, v124
	v_mov_b32_e32 v96, v140
	v_mov_b32_e32 v97, v152
	v_pk_mul_f32 v[98:99], v[98:99], v[98:99]
	v_mov_b32_e32 v100, v127
	v_mov_b32_e32 v101, v151
	v_pk_fma_f32 v[96:97], v[96:97], v[96:97], v[98:99]
	v_mov_b32_e32 v98, v126
	v_mov_b32_e32 v99, v150
	v_pk_mul_f32 v[100:101], v[100:101], v[100:101]
	v_fmamk_f32 v155, v124, 0xba000000, v73
	v_pk_fma_f32 v[98:99], v[98:99], v[98:99], v[100:101]
	v_fmac_f32_e32 v154, 0xba000000, v124
	v_pk_add_f32 v[96:97], v[96:97], v[98:99]
	v_fmamk_f32 v157, v124, 0xba000000, v75
	v_fmac_f32_e32 v156, 0xba000000, v124
	v_pk_add_f32 v[96:97], v[96:97], v[96:97] op_sel_hi:[0,1]
	v_pk_mul_f32 v[98:99], v[156:157], v[156:157]
	v_pk_mul_f32 v[100:101], v[154:155], v[154:155]
	v_fmac_f32_e32 v114, 0xba000000, v124
	v_pk_mov_b32 v[102:103], v[100:101], v[98:99] op_sel:[1,0]
	v_mov_b32_e32 v101, v99
	v_fmamk_f32 v115, v124, 0xba000000, v77
	v_fmac_f32_e32 v116, 0xba000000, v124
	v_mul_f32_e32 v96, v114, v114
	v_pk_add_f32 v[98:99], v[102:103], v[100:101]
	v_fmamk_f32 v117, v124, 0xba000000, v79
	v_pk_fma_f32 v[100:101], v[114:115], v[114:115], v[96:97] op_sel_hi:[1,1,0]
	v_mul_f32_e32 v96, v116, v116
	v_pk_add_f32 v[98:99], v[98:99], v[98:99] op_sel_hi:[0,1]
	v_pk_fma_f32 v[102:103], v[116:117], v[116:117], v[96:97] op_sel_hi:[1,1,0]
	v_fmamk_f32 v109, v124, 0xba000000, v83
	v_fmac_f32_e32 v108, 0xba000000, v124
	v_fmamk_f32 v113, v124, 0xba000000, v81
	v_fmac_f32_e32 v112, 0xba000000, v124
	v_mul_f32_e32 v100, v112, v112
	v_mul_f32_e32 v102, v113, v113
	v_mul_f32_e32 v98, v108, v108
	v_mul_f32_e32 v96, v109, v109
	v_pk_add_f32 v[100:101], v[100:101], v[102:103]
	v_pk_add_f32 v[96:97], v[98:99], v[96:97]
	v_fmamk_f32 v105, v124, 0xba000000, v85
	v_pk_add_f32 v[96:97], v[100:101], v[96:97]
	v_fmac_f32_e32 v104, 0xba000000, v124
	v_fmamk_f32 v107, v124, 0xba000000, v87
	v_fmac_f32_e32 v106, 0xba000000, v124
	v_pk_add_f32 v[110:111], v[96:97], v[96:97] op_sel_hi:[0,1]
	v_pk_mul_f32 v[96:97], v[106:107], v[106:107]
	v_pk_mul_f32 v[98:99], v[104:105], v[104:105]
	v_mov_b32_e32 v102, v90
	v_pk_mov_b32 v[100:101], v[98:99], v[96:97] op_sel:[1,0]
	v_mov_b32_e32 v99, v97
	v_pk_add_f32 v[96:97], v[100:101], v[98:99]
	v_mov_b32_e32 v100, v88
	v_fmac_f32_e32 v100, 0xba000000, v124
	v_pk_add_f32 v[118:119], v[96:97], v[96:97] op_sel_hi:[0,1]
	v_fmamk_f32 v101, v124, 0xba000000, v89
	v_fmac_f32_e32 v102, 0xba000000, v124
	v_mul_f32_e32 v96, v100, v100
	v_fmamk_f32 v103, v124, 0xba000000, v91
	v_pk_fma_f32 v[120:121], v[100:101], v[100:101], v[96:97] op_sel_hi:[1,1,0]
	v_mul_f32_e32 v96, v102, v102
	v_pk_fma_f32 v[122:123], v[102:103], v[102:103], v[96:97] op_sel_hi:[1,1,0]
	v_mov_b32_e32 v96, v94
	v_mov_b32_e32 v98, v92
	v_fmamk_f32 v97, v124, 0xba000000, v95
	v_fmac_f32_e32 v96, 0xba000000, v124
	v_fmamk_f32 v99, v124, 0xba000000, v93
	v_fmac_f32_e32 v98, 0xba000000, v124
	v_mul_f32_e32 v120, v98, v98
	v_mul_f32_e32 v122, v99, v99
	v_mul_f32_e32 v118, v96, v96
	v_mul_f32_e32 v110, v97, v97
	v_pk_add_f32 v[120:121], v[120:121], v[122:123]
	v_pk_add_f32 v[110:111], v[118:119], v[110:111]
	s_nop 0
	v_pk_add_f32 v[110:111], v[120:121], v[110:111]
	s_nop 0
	v_add_f32_e32 v110, v110, v111
	ds_bpermute_b32 v111, v129, v110
	s_waitcnt lgkmcnt(0)
	v_add_f32_e32 v110, v110, v111
	ds_bpermute_b32 v111, v182, v110
	s_waitcnt lgkmcnt(0)
	v_add_f32_e32 v110, v110, v111
	ds_bpermute_b32 v111, v183, v110
	s_waitcnt lgkmcnt(0)
	v_add_f32_e32 v110, v110, v111
	ds_bpermute_b32 v111, v184, v110
	s_waitcnt lgkmcnt(0)
	v_add_f32_e32 v110, v110, v111
	ds_bpermute_b32 v111, v185, v110
	s_waitcnt lgkmcnt(0)
	v_add_f32_e32 v110, v110, v111
	ds_bpermute_b32 v111, v186, v110
	s_waitcnt lgkmcnt(0)
	v_add_f32_e32 v110, v110, v111
	v_fmamk_f32 v110, v110, 0x3a000000, v229
	v_mul_f32_e32 v111, 0x4f800000, v110
	v_cmp_gt_f32_e32 vcc, s4, v110
	s_mov_b32 s4, 0xffff0000
	s_nop 0
	v_cndmask_b32_e32 v110, v110, v111, vcc
	v_sqrt_f32_e32 v111, v110
	s_nop 0
	v_add_u32_e32 v118, -1, v111
	v_fma_f32 v119, -v118, v111, v110
	v_cmp_ge_f32_e64 s[8:9], 0, v119
	v_add_u32_e32 v119, 1, v111
	s_nop 0
	v_cndmask_b32_e64 v118, v111, v118, s[8:9]
	v_fma_f32 v111, -v119, v111, v110
	v_cmp_lt_f32_e64 s[8:9], 0, v111
	s_nop 1
	v_cndmask_b32_e64 v111, v118, v119, s[8:9]
	v_mul_f32_e32 v118, 0x37800000, v111
	v_cndmask_b32_e32 v111, v111, v118, vcc
	v_cmp_class_f32_e32 vcc, v110, v230
	s_nop 1
	v_cndmask_b32_e32 v110, v111, v110, vcc
	v_div_scale_f32 v111, s[8:9], v110, v110, 1.0
	v_rcp_f32_e32 v118, v111
	s_lshl_b64 s[8:9], s[16:17], 11
	v_fma_f32 v119, -v111, v118, 1.0
	v_fmac_f32_e32 v118, v119, v118
	v_div_scale_f32 v119, vcc, 1.0, v110, 1.0
	v_mul_f32_e32 v120, v119, v118
	v_fma_f32 v121, -v111, v120, v119
	v_fmac_f32_e32 v120, v121, v118
	v_fma_f32 v111, -v111, v120, v119
	v_div_fmas_f32 v111, v111, v118, v120
	v_div_fixup_f32 v110, v111, v110, 1.0
	v_add_u32_e32 v111, s6, v187
	ds_read_b128 v[118:121], v111 offset:32768
	ds_read_b128 v[122:125], v111 offset:24576
	v_pk_mul_f32 v[158:159], v[140:141], v[110:111] op_sel_hi:[1,0]
	v_pk_mul_f32 v[126:127], v[126:127], v[110:111] op_sel_hi:[1,0]
	ds_read_b128 v[140:143], v111 offset:33792
	ds_read_b128 v[146:149], v111 offset:25600
	s_waitcnt lgkmcnt(3)
	v_pk_add_f32 v[118:119], v[118:119], 1.0 op_sel_hi:[1,0]
	v_pk_add_f32 v[120:121], v[120:121], 1.0 op_sel_hi:[1,0]
	s_waitcnt lgkmcnt(2)
	v_pk_fma_f32 v[118:119], v[118:119], v[158:159], v[122:123]
	v_pk_fma_f32 v[120:121], v[120:121], v[126:127], v[124:125]
	v_cvt_pk_bf16_f32 v122, v118, v119
	v_cvt_pk_bf16_f32 v123, v120, v121
	v_lshl_add_u64 v[118:119], s[8:9], 1, v[134:135]
	v_pk_mul_f32 v[120:121], v[152:153], v[110:111] op_sel_hi:[1,0]
	s_waitcnt lgkmcnt(1)
	v_pk_add_f32 v[126:127], v[140:141], 1.0 op_sel_hi:[1,0]
	global_store_dwordx2 v[118:119], v[122:123], off
	v_pk_mul_f32 v[122:123], v[150:151], v[110:111] op_sel_hi:[1,0]
	v_pk_add_f32 v[124:125], v[142:143], 1.0 op_sel_hi:[1,0]
	s_waitcnt lgkmcnt(0)
	v_pk_fma_f32 v[120:121], v[126:127], v[120:121], v[146:147]
	v_pk_fma_f32 v[122:123], v[124:125], v[122:123], v[148:149]
	v_cvt_pk_bf16_f32 v120, v120, v121
	v_cvt_pk_bf16_f32 v121, v122, v123
	global_store_dwordx2 v[118:119], v[120:121], off offset:512
	ds_read_b128 v[120:123], v111 offset:34816
	ds_read_b128 v[124:127], v111 offset:26624
	v_pk_mul_f32 v[146:147], v[154:155], v[110:111] op_sel_hi:[1,0]
	v_pk_mul_f32 v[148:149], v[156:157], v[110:111] op_sel_hi:[1,0]
	ds_read_b128 v[140:143], v111 offset:35840
	s_waitcnt lgkmcnt(2)
	v_pk_add_f32 v[152:153], v[120:121], 1.0 op_sel_hi:[1,0]
	v_pk_add_f32 v[150:151], v[122:123], 1.0 op_sel_hi:[1,0]
	s_waitcnt lgkmcnt(1)
	v_pk_fma_f32 v[124:125], v[152:153], v[146:147], v[124:125]
	ds_read_b128 v[120:123], v111 offset:27648
	v_pk_fma_f32 v[126:127], v[150:151], v[148:149], v[126:127]
	v_cvt_pk_bf16_f32 v124, v124, v125
	v_cvt_pk_bf16_f32 v125, v126, v127
	v_pk_mul_f32 v[114:115], v[114:115], v[110:111] op_sel_hi:[1,0]
	s_waitcnt lgkmcnt(1)
	v_pk_add_f32 v[126:127], v[140:141], 1.0 op_sel_hi:[1,0]
	global_store_dwordx2 v[118:119], v[124:125], off offset:1024
	s_waitcnt lgkmcnt(0)
	v_pk_fma_f32 v[114:115], v[126:127], v[114:115], v[120:121]
	v_pk_mul_f32 v[116:117], v[116:117], v[110:111] op_sel_hi:[1,0]
	v_pk_add_f32 v[124:125], v[142:143], 1.0 op_sel_hi:[1,0]
	v_pk_fma_f32 v[116:117], v[124:125], v[116:117], v[122:123]
	v_cvt_pk_bf16_f32 v114, v114, v115
	v_cvt_pk_bf16_f32 v115, v116, v117
	global_store_dwordx2 v[118:119], v[114:115], off offset:1536
	ds_read_b128 v[114:117], v111 offset:36864
	ds_read_b128 v[120:123], v111 offset:28672
	v_pk_mul_f32 v[140:141], v[112:113], v[110:111] op_sel_hi:[1,0]
	v_pk_mul_f32 v[108:109], v[108:109], v[110:111] op_sel_hi:[1,0]
	ds_read_b128 v[124:127], v111 offset:37888
	s_waitcnt lgkmcnt(2)
	v_pk_add_f32 v[116:117], v[116:117], 1.0 op_sel_hi:[1,0]
	v_pk_add_f32 v[142:143], v[114:115], 1.0 op_sel_hi:[1,0]
	s_waitcnt lgkmcnt(1)
	v_pk_fma_f32 v[108:109], v[116:117], v[108:109], v[122:123]
	v_pk_fma_f32 v[116:117], v[142:143], v[140:141], v[120:121]
	ds_read_b128 v[112:115], v111 offset:29696
	v_cvt_pk_bf16_f32 v116, v116, v117
	v_cvt_pk_bf16_f32 v117, v108, v109
	global_store_dwordx2 v[118:119], v[116:117], off offset:2048
	v_pk_mul_f32 v[104:105], v[104:105], v[110:111] op_sel_hi:[1,0]
	s_waitcnt lgkmcnt(1)
	v_pk_add_f32 v[116:117], v[124:125], 1.0 op_sel_hi:[1,0]
	v_pk_mul_f32 v[106:107], v[106:107], v[110:111] op_sel_hi:[1,0]
	v_pk_add_f32 v[108:109], v[126:127], 1.0 op_sel_hi:[1,0]
	s_waitcnt lgkmcnt(0)
	v_pk_fma_f32 v[104:105], v[116:117], v[104:105], v[112:113]
	v_pk_fma_f32 v[106:107], v[108:109], v[106:107], v[114:115]
	v_cvt_pk_bf16_f32 v104, v104, v105
	v_cvt_pk_bf16_f32 v105, v106, v107
	global_store_dwordx2 v[118:119], v[104:105], off offset:2560
	ds_read_b128 v[104:107], v111 offset:38912
	ds_read_b128 v[112:115], v111 offset:30720
	v_pk_mul_f32 v[108:109], v[100:101], v[110:111] op_sel_hi:[1,0]
	v_pk_mul_f32 v[116:117], v[102:103], v[110:111] op_sel_hi:[1,0]
	ds_read_b128 v[100:103], v111 offset:39936
	s_waitcnt lgkmcnt(2)
	v_pk_add_f32 v[122:123], v[104:105], 1.0 op_sel_hi:[1,0]
	v_pk_add_f32 v[120:121], v[106:107], 1.0 op_sel_hi:[1,0]
	s_waitcnt lgkmcnt(1)
	v_pk_fma_f32 v[108:109], v[122:123], v[108:109], v[112:113]
	ds_read_b128 v[104:107], v111 offset:31744
	v_pk_fma_f32 v[114:115], v[120:121], v[116:117], v[114:115]
	v_bfe_u32 v111, v115, 16, 1
	v_add3_u32 v111, v115, v111, s69
	v_pk_mul_f32 v[98:99], v[98:99], v[110:111] op_sel_hi:[1,0]
	s_waitcnt lgkmcnt(1)
	v_pk_add_f32 v[100:101], v[100:101], 1.0 op_sel_hi:[1,0]
	v_pk_mul_f32 v[96:97], v[96:97], v[110:111] op_sel_hi:[1,0]
	s_waitcnt lgkmcnt(0)
	v_pk_fma_f32 v[98:99], v[100:101], v[98:99], v[104:105]
	v_pk_add_f32 v[102:103], v[102:103], 1.0 op_sel_hi:[1,0]
	v_pk_fma_f32 v[96:97], v[102:103], v[96:97], v[106:107]
	v_cvt_pk_bf16_f32 v108, v108, v109
	v_bfe_u32 v109, v114, 16, 1
	v_cvt_pk_bf16_f32 v98, v98, v99
	v_add3_u32 v109, v114, v109, s69
	v_lshrrev_b32_e32 v109, 16, v109
	v_and_or_b32 v109, v111, s4, v109
	v_cvt_pk_bf16_f32 v99, v96, v97
	global_store_dwordx2 v[118:119], v[108:109], off offset:3072
	global_store_dwordx2 v[118:119], v[98:99], off offset:3584
	s_branch .LBB0_1225
